# loop-edge edits: attention 8-step loops' back edge rotated (conditional branch back, continuation block ahead of the header), any-test chain shortened; on top of the epilogue subw de-serialisation
# speedup vs baseline: 1.0076x; 1.0016x over previous
.LBB0_639:
	v_mov_b32_e32 v184, v222
	s_lshl_b32 s2, s0, 2
	v_readfirstlane_b32 s18, v184
	s_ashr_i32 s19, s18, 8
	s_bfe_u32 s22, s18, 0x20006
	s_lshl_b32 s12, s73, 7
	s_or_b32 s2, s2, s74
	s_lshl_b32 s1, s22, 5
	s_lshl_b32 s24, s19, 5
	s_mul_i32 s23, s2, 0x4100
	s_ashr_i32 s25, s12, 31
	s_mul_hi_u32 s13, s2, 0x4100
	s_add_u32 s23, s23, s12
	v_and_b32_e32 v181, 31, v184
	s_addc_u32 s13, s13, s25
	s_or_b32 s23, s23, s1
	v_or_b32_e32 v2, s23, v181
	v_mov_b32_e32 v3, s13
	v_lshlrev_b64 v[2:3], 7, v[2:3]
	v_lshl_add_u64 v[2:3], s[6:7], 0, v[2:3]
	s_ashr_i32 s25, s24, 31
	v_bfe_u32 v180, v184, 5, 1
	v_lshl_add_u64 v[2:3], s[24:25], 1, v[2:3]
	s_mul_i32 s24, s2, 0x208000
	s_mul_hi_u32 s23, s2, 0x208000
	v_lshlrev_b32_e32 v162, 4, v180
	v_mov_b32_e32 v163, v0
	s_add_u32 s26, s11, s24
	v_lshl_add_u64 v[2:3], v[2:3], 0, v[162:163]
	s_addc_u32 s27, s72, s23
	v_ashrrev_i32_e32 v52, 3, v184
	global_load_dwordx4 v[158:161], v[2:3], off
	global_load_dwordx4 v[154:157], v[2:3], off offset:32
	s_add_u32 s28, s36, s24
	v_ashrrev_i32_e32 v53, 31, v52
	v_mov_b64_e32 v[2:3], s[26:27]
	v_lshlrev_b32_e32 v1, 4, v184
	s_addc_u32 s29, s10, s23
	v_lshlrev_b64 v[32:33], 7, v[52:53]
	v_mad_i64_i32 v[2:3], s[26:27], v52, s55, v[2:3]
	v_and_b32_e32 v50, 0x70, v1
	v_mov_b32_e32 v51, v0
	v_lshl_add_u64 v[166:167], v[2:3], 0, v[50:51]
	v_lshl_add_u64 v[2:3], s[28:29], 0, v[32:33]
	v_lshl_add_u64 v[168:169], v[2:3], 0, v[50:51]
	s_nop 1
	v_readfirstlane_b32 s100, v168
	v_readfirstlane_b32 s101, v169
	v_readfirstlane_b32 s98, v166
	v_readfirstlane_b32 s99, v167
	s_nop 1
	v_subrev_u32_e32 v248, s100, v168
	v_subrev_u32_e32 v249, s98, v166
	v_add_co_u32_e32 v46, vcc, s3, v168
	v_mov_b32_e32 v14, v0
	v_mov_b32_e32 v15, v0
	v_addc_co_u32_e32 v47, vcc, 0, v169, vcc
	v_mov_b32_e32 v1, v0
	v_mov_b32_e32 v2, v0
	v_mov_b32_e32 v3, v0
	v_mov_b32_e32 v4, v0
	v_mov_b32_e32 v5, v0
	v_mov_b32_e32 v6, v0
	v_mov_b32_e32 v7, v0
	v_mov_b32_e32 v8, v0
	v_mov_b32_e32 v9, v0
	v_mov_b32_e32 v10, v0
	v_mov_b32_e32 v11, v0
	v_mov_b32_e32 v12, v0
	v_mov_b32_e32 v13, v0
	v_mov_b64_e32 v[30:31], v[14:15]
	v_add_co_u32_e32 v54, vcc, s59, v168
	v_mov_b64_e32 v[28:29], v[12:13]
	v_mov_b64_e32 v[26:27], v[10:11]
	v_mov_b64_e32 v[24:25], v[8:9]
	v_mov_b64_e32 v[22:23], v[6:7]
	v_mov_b64_e32 v[20:21], v[4:5]
	v_mov_b64_e32 v[18:19], v[2:3]
	v_mov_b64_e32 v[16:17], v[0:1]
	v_addc_co_u32_e32 v55, vcc, 0, v169, vcc
	global_load_dwordx4 v[34:37], v[168:169], off
	global_load_dwordx4 v[38:41], v[166:167], off
	global_load_dwordx4 v[42:45], v[166:167], off offset:128
	s_nop 0
	global_load_dwordx4 v[46:49], v[46:47], off
	s_nop 0
	global_load_dwordx4 v[54:57], v[54:55], off
	v_mad_u64_u32 v[164:165], s[26:27], v52, s60, v[50:51]
	v_add_co_u32_e32 v50, vcc, s33, v168
	s_cmp_gt_i32 s73, 1
	v_add_u32_e32 v182, 0, v164
	v_addc_co_u32_e32 v51, vcc, 0, v169, vcc
	s_cselect_b32 s92, 0x8000, s33
	global_load_dwordx4 v[58:61], v[166:167], off offset:256
	global_load_dwordx4 v[62:65], v[50:51], off
	s_cselect_b32 s2, 0x104, 4
	s_mov_b32 s25, 1
	s_add_i32 s13, s2, -1
	s_cmp_lt_i32 s73, 2
	s_barrier
	s_waitcnt vmcnt(5)
	ds_write_b128 v182, v[38:41] offset:36864
	s_waitcnt vmcnt(4)
	ds_write_b128 v182, v[42:45] offset:46080
	ds_write_b128 v182, v[34:37]
	s_waitcnt vmcnt(3)
	ds_write_b128 v182, v[46:49] offset:9216
	s_waitcnt vmcnt(2)
	ds_write_b128 v182, v[54:57] offset:18432
	v_lshl_add_u64 v[34:35], v[168:169], 0, s[92:93]
	s_waitcnt lgkmcnt(0)
	s_barrier
	global_load_dwordx4 v[138:141], v[34:35], off
	global_load_dwordx4 v[142:145], v[166:167], off offset:384
	v_mul_u32_u24_e32 v34, 0x90, v181
	v_add3_u32 v163, 0, v34, v162
	v_lshl_add_u32 v165, s19, 6, v163
	ds_read_b128 v[54:57], v165
	s_waitcnt lgkmcnt(0)
	v_mfma_f32_32x32x16_bf16 v[36:51], v[54:57], v[158:161], v[16:31]
	ds_read_b128 v[54:57], v165 offset:4608
	s_waitcnt lgkmcnt(0)
	v_mfma_f32_32x32x16_bf16 v[16:31], v[54:57], v[158:161], v[16:31]
	ds_read_b128 v[54:57], v165 offset:32
	s_waitcnt lgkmcnt(0)
	v_mfma_f32_32x32x16_bf16 v[36:51], v[54:57], v[154:157], v[36:51]
	ds_read_b128 v[54:57], v165 offset:4640
	v_max3_f32 v34, v36, v37, v38
	s_nop 0
	v_max3_f32 v34, v34, v39, v40
	s_nop 0
	v_max3_f32 v34, v34, v41, v42
	s_nop 0
	v_max3_f32 v34, v34, v43, v44
	s_waitcnt lgkmcnt(0)
	v_mfma_f32_32x32x16_bf16 v[16:31], v[54:57], v[154:157], v[16:31]
	v_max3_f32 v34, v34, v45, v46
	s_nop 0
	v_max3_f32 v34, v34, v47, v48
	s_nop 0
	v_max3_f32 v34, v34, v49, v50
	s_nop 0
	v_max3_f32 v34, v34, v51, v16
	s_nop 0
	v_max3_f32 v34, v34, v17, v18
	s_nop 0
	v_max3_f32 v34, v34, v19, v20
	s_nop 0
	v_max3_f32 v34, v34, v21, v22
	s_nop 0
	v_max3_f32 v34, v34, v23, v24
	s_nop 0
	v_max3_f32 v34, v34, v25, v26
	s_nop 0
	v_max3_f32 v34, v34, v27, v28
	s_nop 0
	v_max3_f32 v34, v34, v29, v30
	s_nop 0
	v_max3_f32 v34, v34, v31, v31
	s_setprio 0
	ds_read_b128 v[54:57], v165 offset:9216
	ds_read_b128 v[106:109], v165 offset:9248
	ds_read_b128 v[110:113], v165 offset:13824
	ds_read_b128 v[114:117], v165 offset:13856
	v_mov_b32_e32 v35, v34
	s_nop 1
	v_permlane32_swap_b32_e32 v34, v35
	v_max_f32_e32 v35, v35, v35
	v_max_f32_e32 v34, v34, v34
	v_max_f32_e32 v35, v34, v35
	v_add_f32_e32 v183, 0, v35
	v_xor_b32_e32 v34, 0x80000000, v183
	v_sub_f32_e32 v53, v36, v35
	v_sub_f32_e32 v16, v16, v35
	v_sub_f32_e32 v66, v37, v35
	v_sub_f32_e32 v17, v17, v35
	v_sub_f32_e32 v67, v38, v35
	v_sub_f32_e32 v18, v18, v35
	v_sub_f32_e32 v68, v39, v35
	v_sub_f32_e32 v19, v19, v35
	v_sub_f32_e32 v69, v40, v35
	v_sub_f32_e32 v20, v20, v35
	v_sub_f32_e32 v70, v41, v35
	v_sub_f32_e32 v21, v21, v35
	v_sub_f32_e32 v71, v42, v35
	v_sub_f32_e32 v22, v22, v35
	v_sub_f32_e32 v72, v43, v35
	v_sub_f32_e32 v23, v23, v35
	v_sub_f32_e32 v118, v44, v35
	v_sub_f32_e32 v24, v24, v35
	v_sub_f32_e32 v119, v45, v35
	v_sub_f32_e32 v25, v25, v35
	v_sub_f32_e32 v120, v46, v35
	v_sub_f32_e32 v26, v26, v35
	v_sub_f32_e32 v121, v47, v35
	v_sub_f32_e32 v27, v27, v35
	v_sub_f32_e32 v122, v48, v35
	v_sub_f32_e32 v28, v28, v35
	v_sub_f32_e32 v123, v49, v35
	v_sub_f32_e32 v29, v29, v35
	v_sub_f32_e32 v50, v50, v35
	v_sub_f32_e32 v30, v30, v35
	v_sub_f32_e32 v51, v51, v35
	v_sub_f32_e32 v31, v31, v35
	v_mov_b32_e32 v35, v34
	v_mov_b32_e32 v36, v34
	v_mov_b32_e32 v37, v34
	v_mov_b32_e32 v38, v34
	v_mov_b32_e32 v39, v34
	v_mov_b32_e32 v40, v34
	v_mov_b32_e32 v41, v34
	v_mov_b32_e32 v42, v34
	v_mov_b32_e32 v43, v34
	v_mov_b32_e32 v44, v34
	v_mov_b32_e32 v45, v34
	v_mov_b32_e32 v46, v34
	v_mov_b32_e32 v47, v34
	v_mov_b32_e32 v48, v34
	v_mov_b32_e32 v49, v34
	s_waitcnt lgkmcnt(3)
	s_nop 4
	v_mfma_f32_32x32x16_bf16 v[82:97], v[54:57], v[158:161], v[34:49]
	v_exp_f32_e32 v102, v53
	v_exp_f32_e32 v103, v66
	v_exp_f32_e32 v104, v67
	v_exp_f32_e32 v105, v68
	s_nop 0
	v_exp_f32_e32 v98, v69
	v_exp_f32_e32 v99, v70
	v_exp_f32_e32 v100, v71
	v_exp_f32_e32 v101, v72
	s_nop 0
	s_waitcnt lgkmcnt(1)
	s_nop 4
	v_mfma_f32_32x32x16_bf16 v[66:81], v[110:113], v[158:161], v[34:49]
	v_exp_f32_e32 v194, v118
	v_exp_f32_e32 v187, v119
	v_exp_f32_e32 v186, v120
	v_exp_f32_e32 v185, v121
	s_nop 0
	v_exp_f32_e32 v133, v122
	v_exp_f32_e32 v132, v123
	v_exp_f32_e32 v131, v50
	v_exp_f32_e32 v130, v51
	s_nop 0
	v_mfma_f32_32x32x16_bf16 v[82:97], v[106:109], v[154:157], v[82:97]
	v_exp_f32_e32 v129, v16
	v_exp_f32_e32 v128, v17
	v_exp_f32_e32 v127, v18
	v_exp_f32_e32 v126, v19
	s_nop 0
	v_exp_f32_e32 v125, v20
	v_exp_f32_e32 v124, v21
	v_exp_f32_e32 v123, v22
	v_exp_f32_e32 v122, v23
	s_nop 0
	s_waitcnt lgkmcnt(0)
	v_mfma_f32_32x32x16_bf16 v[66:81], v[114:117], v[154:157], v[66:81]
	v_exp_f32_e32 v109, v24
	v_exp_f32_e32 v108, v25
	v_exp_f32_e32 v107, v26
	v_exp_f32_e32 v106, v27
	s_nop 0
	v_exp_f32_e32 v113, v28
	v_exp_f32_e32 v112, v29
	v_exp_f32_e32 v111, v30
	v_exp_f32_e32 v110, v31
	s_nop 0
	s_waitcnt vmcnt(2)
	ds_write_b128 v182, v[62:65] offset:27648
	ds_write_b128 v182, v[58:61] offset:55296
	s_cbranch_scc1 .LBB0_665
	s_add_u32 s24, s4, s24
	v_and_b32_e32 v18, 7, v184
	s_addc_u32 s25, s5, s23
	v_mad_i64_i32 v[16:17], s[26:27], v52, s55, 0
	v_lshlrev_b32_e32 v170, 4, v18
	v_lshl_add_u64 v[174:175], s[24:25], 0, v[32:33]
	v_mov_b64_e32 v[32:33], v[14:15]
	v_lshl_add_u64 v[172:173], s[24:25], 0, v[16:17]
	v_mov_b64_e32 v[30:31], v[12:13]
	v_mov_b64_e32 v[28:29], v[10:11]
	v_mov_b64_e32 v[26:27], v[8:9]
	v_mov_b64_e32 v[24:25], v[6:7]
	v_mov_b64_e32 v[22:23], v[4:5]
	v_mov_b64_e32 v[20:21], v[2:3]
	v_mov_b64_e32 v[18:19], v[0:1]
	v_mov_b64_e32 v[16:17], v[14:15]
	v_mov_b32_e32 v171, v0
	s_mov_b32 s25, 1
	v_mov_b32_e32 v50, 0
	s_mov_b32 s23, 12
	v_mov_b64_e32 v[14:15], v[12:13]
	v_mov_b64_e32 v[12:13], v[10:11]
	v_mov_b64_e32 v[10:11], v[8:9]
	v_mov_b64_e32 v[8:9], v[6:7]
	v_mov_b64_e32 v[6:7], v[4:5]
	v_mov_b64_e32 v[4:5], v[2:3]
	v_mov_b64_e32 v[2:3], v[0:1]
	s_branch .LBB0_641
.Lle_a0_cont:
	s_mov_b32 s23, s26
.LBB0_641:
	s_add_i32 s24, s23, -7
	s_lshl_b32 s92, s24, 13
	s_add_u32 vcc_lo, s100, s92
	s_addc_u32 vcc_hi, s101, 0
	global_load_dwordx4 v[52:55], v248, vcc
	s_add_i32 s24, s23, -8
	s_lshl_b32 s92, s24, 7
	s_add_u32 vcc_lo, s98, s92
	s_addc_u32 vcc_hi, s99, 0
	global_load_dwordx4 v[56:59], v249, vcc
	s_mul_i32 s26, s25, 0x2400
	s_add_i32 s24, s23, -7
	s_add_i32 s27, s26, 0xffffdc00
	s_cmp_lg_u32 s25, 0
	s_cselect_b32 s27, s27, 0x9000
	v_add_u32_e32 v1, s27, v163
	ds_read_b128 v[60:63], v1 offset:36864
	ds_read_b128 v[114:117], v1 offset:36896
	ds_read_b128 v[118:121], v1 offset:41472
	ds_read_b128 v[134:137], v1 offset:41504
	ds_read_b128 v[146:149], v1 offset:36928
	ds_read_b128 v[150:153], v1 offset:36960
	ds_read_b128 v[196:199], v1 offset:41536
	ds_read_b128 v[200:203], v1 offset:41568
	s_setprio 3
	v_cvt_pk_bf16_f32 v204, v102, v103
	v_cvt_pk_bf16_f32 v205, v104, v105
	v_cvt_pk_bf16_f32 v206, v98, v99
	v_cvt_pk_bf16_f32 v207, v100, v101
	s_waitcnt lgkmcnt(7)
	s_nop 0
	v_mfma_f32_32x32x16_bf16 v[18:33], v[60:63], v[204:207], v[18:33]
	v_add_f32_e32 v1, v102, v103
	v_add_f32_e32 v1, v1, v104
	v_add_f32_e32 v1, v1, v105
	s_waitcnt lgkmcnt(5)
	v_mfma_f32_32x32x16_bf16 v[2:17], v[118:121], v[204:207], v[2:17]
	v_cvt_pk_bf16_f32 v60, v194, v187
	v_cvt_pk_bf16_f32 v61, v186, v185
	v_cvt_pk_bf16_f32 v62, v133, v132
	v_cvt_pk_bf16_f32 v63, v131, v130
	v_add_f32_e32 v1, v1, v98
	v_add_f32_e32 v1, v1, v99
	v_add_f32_e32 v1, v1, v100
	v_add_f32_e32 v1, v1, v101
	s_nop 0
	v_mfma_f32_32x32x16_bf16 v[18:33], v[114:117], v[60:63], v[18:33]
	v_add_f32_e32 v1, v1, v194
	v_add_f32_e32 v1, v1, v187
	v_add_f32_e32 v1, v1, v186
	v_add_f32_e32 v1, v1, v185
	s_waitcnt lgkmcnt(4)
	v_mfma_f32_32x32x16_bf16 v[2:17], v[134:137], v[60:63], v[2:17]
	v_cvt_pk_bf16_f32 v98, v129, v128
	v_cvt_pk_bf16_f32 v99, v127, v126
	v_cvt_pk_bf16_f32 v100, v125, v124
	v_cvt_pk_bf16_f32 v101, v123, v122
	v_add_f32_e32 v1, v1, v133
	v_add_f32_e32 v1, v1, v132
	v_add_f32_e32 v1, v1, v131
	v_add_f32_e32 v1, v1, v130
	s_waitcnt lgkmcnt(3)
	v_mfma_f32_32x32x16_bf16 v[18:33], v[146:149], v[98:101], v[18:33]
	v_add_f32_e32 v1, v1, v129
	v_add_f32_e32 v1, v1, v128
	v_add_f32_e32 v1, v1, v127
	v_add_f32_e32 v1, v1, v126
	s_waitcnt lgkmcnt(1)
	v_mfma_f32_32x32x16_bf16 v[2:17], v[196:199], v[98:101], v[2:17]
	v_cvt_pk_bf16_f32 v60, v109, v108
	v_cvt_pk_bf16_f32 v61, v107, v106
	v_cvt_pk_bf16_f32 v62, v113, v112
	v_cvt_pk_bf16_f32 v63, v111, v110
	v_add_f32_e32 v1, v1, v125
	v_add_f32_e32 v1, v1, v124
	v_add_f32_e32 v1, v1, v123
	v_add_f32_e32 v1, v1, v122
	s_nop 0
	v_mfma_f32_32x32x16_bf16 v[18:33], v[150:153], v[60:63], v[18:33]
	v_add_f32_e32 v1, v1, v109
	v_add_f32_e32 v1, v1, v108
	v_add_f32_e32 v1, v1, v107
	v_add_f32_e32 v1, v1, v106
	s_waitcnt lgkmcnt(0)
	v_mfma_f32_32x32x16_bf16 v[2:17], v[200:203], v[60:63], v[2:17]
	v_add_f32_e32 v1, v1, v113
	v_add_f32_e32 v1, v1, v112
	v_add_f32_e32 v1, v1, v111
	v_add_f32_e32 v1, v1, v110
	s_setprio 2
	s_waitcnt lgkmcnt(0)
	s_barrier
	ds_read_b128 v[240:243], v165 offset:18432
	ds_read_b128 v[244:247], v165 offset:23040
	ds_read_b128 v[130:133], v165 offset:18464
	ds_read_b128 v[146:149], v165 offset:23072
	v_exp_f32_e32 v185, v82
	v_exp_f32_e32 v186, v83
	v_exp_f32_e32 v187, v84
	v_exp_f32_e32 v194, v85
	v_exp_f32_e32 v195, v86
	v_exp_f32_e32 v196, v87
	v_exp_f32_e32 v197, v88
	v_exp_f32_e32 v198, v89
	s_waitcnt lgkmcnt(2)
	v_mfma_f32_32x32x16_bf16 v[114:129], v[240:243], v[158:161], v[34:49]
	s_waitcnt lgkmcnt(1)
	v_mfma_f32_32x32x16_bf16 v[98:113], v[244:247], v[158:161], v[34:49]
	v_exp_f32_e32 v199, v90
	v_exp_f32_e32 v200, v91
	v_exp_f32_e32 v201, v92
	v_exp_f32_e32 v202, v93
	v_exp_f32_e32 v134, v94
	v_exp_f32_e32 v135, v95
	v_exp_f32_e32 v136, v96
	v_exp_f32_e32 v137, v97
	v_mfma_f32_32x32x16_bf16 v[114:129], v[130:133], v[154:157], v[114:129]
	v_exp_f32_e32 v96, v66
	v_exp_f32_e32 v97, v67
	v_exp_f32_e32 v203, v68
	v_exp_f32_e32 v204, v69
	v_exp_f32_e32 v130, v70
	v_exp_f32_e32 v131, v71
	v_exp_f32_e32 v132, v72
	v_exp_f32_e32 v133, v73
	s_waitcnt lgkmcnt(0)
	v_mfma_f32_32x32x16_bf16 v[98:113], v[146:149], v[154:157], v[98:113]
	v_exp_f32_e32 v205, v74
	v_exp_f32_e32 v206, v75
	v_exp_f32_e32 v207, v76
	v_exp_f32_e32 v208, v77
	v_exp_f32_e32 v209, v78
	v_exp_f32_e32 v210, v79
	v_exp_f32_e32 v211, v80
	v_exp_f32_e32 v212, v81
	v_add_u32_e32 v88, s26, v163
	ds_read_b128 v[240:243], v165 offset:27648
	ds_read_b128 v[244:247], v165 offset:32256
	ds_read_b128 v[60:63], v88 offset:41472
	ds_read_b128 v[64:67], v88 offset:36864
	ds_read_b128 v[68:71], v88 offset:36896
	ds_read_b128 v[72:75], v88 offset:41504
	ds_read_b128 v[76:79], v88 offset:36928
	ds_read_b128 v[80:83], v88 offset:41536
	ds_read_b128 v[84:87], v88 offset:36960
	ds_read_b128 v[88:91], v88 offset:41568
	s_cmp_gt_i32 s25, 2
	s_cselect_b32 s27, -3, 2
	s_add_i32 s27, s27, s25
	s_add_i32 s26, s23, -6
	s_mulk_i32 s27, 0x2400
	s_min_u32 s26, s26, s13
	v_add_u32_e32 v51, s27, v182
	s_min_u32 s24, s24, s13
	s_lshl_b32 s92, s26, 13
	s_waitcnt vmcnt(3)
	ds_write_b128 v182, v[138:141]
	s_waitcnt vmcnt(2)
	ds_write_b128 v51, v[142:145] offset:36864
	v_add_f32_e32 v1, v50, v1
	s_add_u32 vcc_lo, s100, s92
	s_addc_u32 vcc_hi, s101, 0
	global_load_dwordx4 v[146:149], v248, vcc
	s_lshl_b32 s92, s24, 7
	s_add_u32 vcc_lo, s98, s92
	s_addc_u32 vcc_hi, s99, 0
	global_load_dwordx4 v[150:153], v249, vcc
	s_add_i32 s27, s25, 1
	s_setprio 1
	v_cvt_pk_bf16_f32 v92, v185, v186
	v_cvt_pk_bf16_f32 v93, v187, v194
	v_cvt_pk_bf16_f32 v94, v195, v196
	v_cvt_pk_bf16_f32 v95, v197, v198
	s_waitcnt lgkmcnt(8)
	s_nop 0
	v_mfma_f32_32x32x16_bf16 v[18:33], v[64:67], v[92:95], v[18:33]
	v_add_f32_e32 v213, v185, v186
	v_add_f32_e32 v213, v213, v187
	v_add_f32_e32 v213, v213, v194
	s_nop 0
	v_mfma_f32_32x32x16_bf16 v[2:17], v[60:63], v[92:95], v[2:17]
	v_cvt_pk_bf16_f32 v64, v199, v200
	v_cvt_pk_bf16_f32 v65, v201, v202
	v_cvt_pk_bf16_f32 v66, v134, v135
	v_cvt_pk_bf16_f32 v67, v136, v137
	v_add_f32_e32 v213, v213, v195
	v_add_f32_e32 v213, v213, v196
	v_add_f32_e32 v213, v213, v197
	v_add_f32_e32 v213, v213, v198
	s_waitcnt lgkmcnt(7)
	v_mfma_f32_32x32x16_bf16 v[18:33], v[68:71], v[64:67], v[18:33]
	v_add_f32_e32 v213, v213, v199
	v_add_f32_e32 v213, v213, v200
	v_add_f32_e32 v213, v213, v201
	v_add_f32_e32 v213, v213, v202
	s_waitcnt lgkmcnt(6)
	v_mfma_f32_32x32x16_bf16 v[2:17], v[72:75], v[64:67], v[2:17]
	v_cvt_pk_bf16_f32 v60, v96, v97
	v_cvt_pk_bf16_f32 v61, v203, v204
	v_cvt_pk_bf16_f32 v62, v130, v131
	v_cvt_pk_bf16_f32 v63, v132, v133
	v_add_f32_e32 v213, v213, v134
	v_add_f32_e32 v213, v213, v135
	v_add_f32_e32 v213, v213, v136
	v_add_f32_e32 v213, v213, v137
	s_waitcnt lgkmcnt(5)
	v_mfma_f32_32x32x16_bf16 v[18:33], v[76:79], v[60:63], v[18:33]
	v_add_f32_e32 v213, v213, v96
	v_add_f32_e32 v213, v213, v97
	v_add_f32_e32 v213, v213, v203
	v_add_f32_e32 v213, v213, v204
	s_waitcnt lgkmcnt(4)
	v_mfma_f32_32x32x16_bf16 v[2:17], v[80:83], v[60:63], v[2:17]
	v_cvt_pk_bf16_f32 v64, v205, v206
	v_cvt_pk_bf16_f32 v65, v207, v208
	v_cvt_pk_bf16_f32 v66, v209, v210
	v_cvt_pk_bf16_f32 v67, v211, v212
	v_add_f32_e32 v213, v213, v130
	v_add_f32_e32 v213, v213, v131
	v_add_f32_e32 v213, v213, v132
	v_add_f32_e32 v213, v213, v133
	s_waitcnt lgkmcnt(3)
	v_mfma_f32_32x32x16_bf16 v[18:33], v[84:87], v[64:67], v[18:33]
	v_add_f32_e32 v213, v213, v205
	v_add_f32_e32 v213, v213, v206
	v_add_f32_e32 v213, v213, v207
	v_add_f32_e32 v213, v213, v208
	s_waitcnt lgkmcnt(2)
	v_mfma_f32_32x32x16_bf16 v[2:17], v[88:91], v[64:67], v[2:17]
	v_add_f32_e32 v213, v213, v209
	v_add_f32_e32 v213, v213, v210
	v_add_f32_e32 v213, v213, v211
	v_add_f32_e32 v213, v213, v212
	s_setprio 0
	ds_read_b128 v[64:67], v165 offset:27680
	ds_read_b128 v[72:75], v165 offset:32288
	s_cmp_lg_u32 s25, 4
	s_cselect_b32 s24, s27, 0
	s_waitcnt lgkmcnt(2)
	v_mfma_f32_32x32x16_bf16 v[130:145], v[240:243], v[158:161], v[34:49]
	v_exp_f32_e32 v185, v114
	v_exp_f32_e32 v186, v115
	v_exp_f32_e32 v187, v116
	v_exp_f32_e32 v194, v117
	v_exp_f32_e32 v195, v118
	v_exp_f32_e32 v196, v119
	v_exp_f32_e32 v197, v120
	v_exp_f32_e32 v198, v121
	s_waitcnt lgkmcnt(1)
	v_mfma_f32_32x32x16_bf16 v[82:97], v[244:247], v[158:161], v[34:49]
	v_exp_f32_e32 v199, v122
	v_exp_f32_e32 v200, v123
	v_exp_f32_e32 v201, v124
	v_exp_f32_e32 v202, v125
	v_exp_f32_e32 v122, v126
	v_exp_f32_e32 v123, v127
	v_exp_f32_e32 v124, v128
	v_exp_f32_e32 v125, v129
	v_mfma_f32_32x32x16_bf16 v[130:145], v[64:67], v[154:157], v[130:145]
	v_exp_f32_e32 v126, v98
	v_exp_f32_e32 v127, v99
	v_exp_f32_e32 v128, v100
	v_exp_f32_e32 v129, v101
	v_exp_f32_e32 v203, v102
	v_exp_f32_e32 v204, v103
	v_exp_f32_e32 v205, v104
	v_exp_f32_e32 v206, v105
	s_waitcnt lgkmcnt(0)
	v_mfma_f32_32x32x16_bf16 v[82:97], v[72:75], v[154:157], v[82:97]
	v_exp_f32_e32 v102, v106
	v_exp_f32_e32 v103, v107
	v_exp_f32_e32 v104, v108
	v_exp_f32_e32 v105, v109
	v_exp_f32_e32 v106, v110
	v_exp_f32_e32 v107, v111
	v_exp_f32_e32 v108, v112
	v_exp_f32_e32 v109, v113
	s_cmp_gt_i32 s24, 2
	s_cselect_b32 s25, -3, 2
	s_add_i32 s25, s25, s24
	s_mulk_i32 s25, 0x2400
	v_add_u32_e32 v50, s25, v182
	s_add_i32 s25, s24, 1
	s_cmp_lg_u32 s24, 4
	s_cselect_b32 s24, s25, 0
	s_add_i32 s25, s23, -5
	s_min_u32 s25, s25, s13
	s_lshl_b32 s92, s25, 13
	s_waitcnt vmcnt(3)
	ds_write_b128 v182, v[52:55] offset:9216
	s_waitcnt vmcnt(2)
	ds_write_b128 v50, v[56:59] offset:36864
	s_add_u32 vcc_lo, s100, s92
	s_addc_u32 vcc_hi, s101, 0
	global_load_dwordx4 v[118:121], v248, vcc
	s_lshl_b32 s92, s26, 7
	s_add_u32 vcc_lo, s98, s92
	s_addc_u32 vcc_hi, s99, 0
	global_load_dwordx4 v[114:117], v249, vcc
	s_mul_i32 s26, s24, 0x2400
	s_add_i32 s27, s26, 0xffffdc00
	s_cmp_lg_u32 s24, 0
	s_cselect_b32 s27, s27, 0x9000
	v_add_u32_e32 v78, s27, v163
	ds_read_b128 v[50:53], v78 offset:36864
	ds_read_b128 v[54:57], v78 offset:36896
	ds_read_b128 v[58:61], v78 offset:41472
	ds_read_b128 v[62:65], v78 offset:41504
	ds_read_b128 v[66:69], v78 offset:36928
	ds_read_b128 v[70:73], v78 offset:36960
	ds_read_b128 v[74:77], v78 offset:41536
	ds_read_b128 v[78:81], v78 offset:41568
	s_setprio 3
	v_cvt_pk_bf16_f32 v98, v185, v186
	v_cvt_pk_bf16_f32 v99, v187, v194
	v_cvt_pk_bf16_f32 v100, v195, v196
	v_cvt_pk_bf16_f32 v101, v197, v198
	s_waitcnt lgkmcnt(7)
	s_nop 0
	v_mfma_f32_32x32x16_bf16 v[18:33], v[50:53], v[98:101], v[18:33]
	v_add_f32_e32 v110, v185, v186
	v_add_f32_e32 v110, v110, v187
	v_add_f32_e32 v110, v110, v194
	s_waitcnt lgkmcnt(5)
	v_mfma_f32_32x32x16_bf16 v[2:17], v[58:61], v[98:101], v[2:17]
	v_cvt_pk_bf16_f32 v50, v199, v200
	v_cvt_pk_bf16_f32 v51, v201, v202
	v_cvt_pk_bf16_f32 v52, v122, v123
	v_cvt_pk_bf16_f32 v53, v124, v125
	v_add_f32_e32 v110, v110, v195
	v_add_f32_e32 v110, v110, v196
	v_add_f32_e32 v110, v110, v197
	v_add_f32_e32 v110, v110, v198
	s_nop 0
	v_mfma_f32_32x32x16_bf16 v[18:33], v[54:57], v[50:53], v[18:33]
	v_add_f32_e32 v110, v110, v199
	v_add_f32_e32 v110, v110, v200
	v_add_f32_e32 v110, v110, v201
	v_add_f32_e32 v110, v110, v202
	s_waitcnt lgkmcnt(4)
	v_mfma_f32_32x32x16_bf16 v[2:17], v[62:65], v[50:53], v[2:17]
	v_cvt_pk_bf16_f32 v54, v126, v127
	v_cvt_pk_bf16_f32 v55, v128, v129
	v_cvt_pk_bf16_f32 v56, v203, v204
	v_cvt_pk_bf16_f32 v57, v205, v206
	v_add_f32_e32 v110, v110, v122
	v_add_f32_e32 v110, v110, v123
	v_add_f32_e32 v110, v110, v124
	v_add_f32_e32 v110, v110, v125
	s_waitcnt lgkmcnt(3)
	v_mfma_f32_32x32x16_bf16 v[18:33], v[66:69], v[54:57], v[18:33]
	v_add_f32_e32 v110, v110, v126
	v_add_f32_e32 v110, v110, v127
	v_add_f32_e32 v110, v110, v128
	v_add_f32_e32 v110, v110, v129
	s_waitcnt lgkmcnt(1)
	v_mfma_f32_32x32x16_bf16 v[2:17], v[74:77], v[54:57], v[2:17]
	v_cvt_pk_bf16_f32 v50, v102, v103
	v_cvt_pk_bf16_f32 v51, v104, v105
	v_cvt_pk_bf16_f32 v52, v106, v107
	v_cvt_pk_bf16_f32 v53, v108, v109
	v_add_f32_e32 v110, v110, v203
	v_add_f32_e32 v110, v110, v204
	v_add_f32_e32 v110, v110, v205
	v_add_f32_e32 v110, v110, v206
	s_nop 0
	v_mfma_f32_32x32x16_bf16 v[18:33], v[70:73], v[50:53], v[18:33]
	v_add_f32_e32 v110, v110, v102
	v_add_f32_e32 v110, v110, v103
	v_add_f32_e32 v110, v110, v104
	v_add_f32_e32 v110, v110, v105
	s_waitcnt lgkmcnt(0)
	v_mfma_f32_32x32x16_bf16 v[2:17], v[78:81], v[50:53], v[2:17]
	v_add_f32_e32 v110, v110, v106
	v_add_f32_e32 v110, v110, v107
	v_add_f32_e32 v110, v110, v108
	v_add_f32_e32 v110, v110, v109
	s_setprio 2
	s_waitcnt lgkmcnt(0)
	s_barrier
	ds_read_b128 v[240:243], v165
	ds_read_b128 v[244:247], v165 offset:4608
	ds_read_b128 v[102:105], v165 offset:32
	ds_read_b128 v[106:109], v165 offset:4640
	v_add_f32_e32 v1, v1, v213
	v_exp_f32_e32 v185, v130
	v_exp_f32_e32 v186, v131
	v_exp_f32_e32 v187, v132
	v_exp_f32_e32 v194, v133
	v_exp_f32_e32 v195, v134
	v_exp_f32_e32 v196, v135
	v_exp_f32_e32 v197, v136
	v_exp_f32_e32 v198, v137
	s_waitcnt lgkmcnt(2)
	v_mfma_f32_32x32x16_bf16 v[66:81], v[240:243], v[158:161], v[34:49]
	v_mfma_f32_32x32x16_bf16 v[50:65], v[244:247], v[158:161], v[34:49]
	v_exp_f32_e32 v134, v138
	v_exp_f32_e32 v135, v139
	v_exp_f32_e32 v136, v140
	v_exp_f32_e32 v137, v141
	v_exp_f32_e32 v138, v142
	v_exp_f32_e32 v139, v143
	v_exp_f32_e32 v140, v144
	v_exp_f32_e32 v141, v145
	s_waitcnt lgkmcnt(1)
	v_mfma_f32_32x32x16_bf16 v[66:81], v[102:105], v[154:157], v[66:81]
	v_exp_f32_e32 v142, v82
	v_exp_f32_e32 v143, v83
	v_exp_f32_e32 v144, v84
	v_exp_f32_e32 v145, v85
	v_exp_f32_e32 v199, v86
	v_exp_f32_e32 v200, v87
	v_exp_f32_e32 v201, v88
	v_exp_f32_e32 v202, v89
	s_waitcnt lgkmcnt(0)
	v_mfma_f32_32x32x16_bf16 v[50:65], v[106:109], v[154:157], v[50:65]
	v_exp_f32_e32 v203, v90
	v_exp_f32_e32 v204, v91
	v_exp_f32_e32 v205, v92
	v_exp_f32_e32 v206, v93
	v_exp_f32_e32 v207, v94
	v_exp_f32_e32 v208, v95
	v_exp_f32_e32 v209, v96
	v_exp_f32_e32 v210, v97
	v_add_f32_e32 v1, v1, v110
	v_add_u32_e32 v111, s26, v163
	ds_read_b128 v[240:243], v165 offset:9216
	ds_read_b128 v[244:247], v165 offset:13824
	ds_read_b128 v[82:85], v111 offset:41472
	ds_read_b128 v[86:89], v111 offset:36864
	ds_read_b128 v[90:93], v111 offset:36896
	ds_read_b128 v[94:97], v111 offset:41504
	ds_read_b128 v[98:101], v111 offset:36928
	ds_read_b128 v[102:105], v111 offset:41536
	ds_read_b128 v[106:109], v111 offset:36960
	ds_read_b128 v[110:113], v111 offset:41568
	s_cmp_gt_i32 s24, 2
	s_cselect_b32 s27, -3, 2
	s_add_i32 s27, s27, s24
	s_mulk_i32 s27, 0x2400
	v_add_u32_e32 v250, s27, v182
	s_mov_b32 s27, 0x18950000
	s_waitcnt vmcnt(3)
	ds_write_b128 v182, v[146:149] offset:18432
	s_waitcnt vmcnt(2)
	ds_write_b128 v250, v[150:153] offset:36864
	s_add_i32 s92, s23, -4
	s_lshl_b32 s92, s92, 13
	s_add_u32 vcc_lo, s100, s92
	s_addc_u32 vcc_hi, s101, 0
	global_load_dwordx4 v[126:129], v248, vcc
	s_lshl_b32 s92, s25, 7
	s_add_u32 vcc_lo, s98, s92
	s_addc_u32 vcc_hi, s99, 0
	global_load_dwordx4 v[122:125], v249, vcc
	s_add_i32 s26, s24, 1
	s_setprio 1
	v_cvt_pk_bf16_f32 v130, v185, v186
	v_cvt_pk_bf16_f32 v131, v187, v194
	v_cvt_pk_bf16_f32 v132, v195, v196
	v_cvt_pk_bf16_f32 v133, v197, v198
	s_waitcnt lgkmcnt(8)
	s_nop 0
	v_mfma_f32_32x32x16_bf16 v[18:33], v[86:89], v[130:133], v[18:33]
	v_add_f32_e32 v146, v185, v186
	v_add_f32_e32 v146, v146, v187
	v_add_f32_e32 v146, v146, v194
	s_nop 0
	v_mfma_f32_32x32x16_bf16 v[2:17], v[82:85], v[130:133], v[2:17]
	v_cvt_pk_bf16_f32 v86, v134, v135
	v_cvt_pk_bf16_f32 v87, v136, v137
	v_cvt_pk_bf16_f32 v88, v138, v139
	v_cvt_pk_bf16_f32 v89, v140, v141
	v_add_f32_e32 v146, v146, v195
	v_add_f32_e32 v146, v146, v196
	v_add_f32_e32 v146, v146, v197
	v_add_f32_e32 v146, v146, v198
	s_waitcnt lgkmcnt(7)
	v_mfma_f32_32x32x16_bf16 v[18:33], v[90:93], v[86:89], v[18:33]
	v_add_f32_e32 v146, v146, v134
	v_add_f32_e32 v146, v146, v135
	v_add_f32_e32 v146, v146, v136
	v_add_f32_e32 v146, v146, v137
	s_waitcnt lgkmcnt(6)
	v_mfma_f32_32x32x16_bf16 v[2:17], v[94:97], v[86:89], v[2:17]
	v_cvt_pk_bf16_f32 v82, v142, v143
	v_cvt_pk_bf16_f32 v83, v144, v145
	v_cvt_pk_bf16_f32 v84, v199, v200
	v_cvt_pk_bf16_f32 v85, v201, v202
	v_add_f32_e32 v146, v146, v138
	v_add_f32_e32 v146, v146, v139
	v_add_f32_e32 v146, v146, v140
	v_add_f32_e32 v146, v146, v141
	s_waitcnt lgkmcnt(5)
	v_mfma_f32_32x32x16_bf16 v[18:33], v[98:101], v[82:85], v[18:33]
	v_add_f32_e32 v146, v146, v142
	v_add_f32_e32 v146, v146, v143
	v_add_f32_e32 v146, v146, v144
	v_add_f32_e32 v146, v146, v145
	s_waitcnt lgkmcnt(4)
	v_mfma_f32_32x32x16_bf16 v[2:17], v[102:105], v[82:85], v[2:17]
	v_cvt_pk_bf16_f32 v86, v203, v204
	v_cvt_pk_bf16_f32 v87, v205, v206
	v_cvt_pk_bf16_f32 v88, v207, v208
	v_cvt_pk_bf16_f32 v89, v209, v210
	v_add_f32_e32 v146, v146, v199
	v_add_f32_e32 v146, v146, v200
	v_add_f32_e32 v146, v146, v201
	v_add_f32_e32 v146, v146, v202
	s_waitcnt lgkmcnt(3)
	v_mfma_f32_32x32x16_bf16 v[18:33], v[106:109], v[86:89], v[18:33]
	v_add_f32_e32 v146, v146, v203
	v_add_f32_e32 v146, v146, v204
	v_add_f32_e32 v146, v146, v205
	v_add_f32_e32 v146, v146, v206
	s_waitcnt lgkmcnt(2)
	v_mfma_f32_32x32x16_bf16 v[2:17], v[110:113], v[86:89], v[2:17]
	v_add_f32_e32 v146, v146, v207
	v_add_f32_e32 v146, v146, v208
	v_add_f32_e32 v146, v146, v209
	v_add_f32_e32 v146, v146, v210
	s_setprio 0
	ds_read_b128 v[130:133], v165 offset:9248
	ds_read_b128 v[138:141], v165 offset:13856
	s_cmp_lg_u32 s24, 4
	s_cselect_b32 s24, s26, 0
	s_waitcnt lgkmcnt(2)
	v_mfma_f32_32x32x16_bf16 v[98:113], v[240:243], v[158:161], v[34:49]
	v_exp_f32_e32 v142, v66
	v_exp_f32_e32 v143, v67
	v_exp_f32_e32 v144, v68
	v_exp_f32_e32 v145, v69
	v_exp_f32_e32 v147, v70
	v_exp_f32_e32 v148, v71
	v_exp_f32_e32 v149, v72
	v_exp_f32_e32 v150, v73
	s_waitcnt lgkmcnt(1)
	v_mfma_f32_32x32x16_bf16 v[82:97], v[244:247], v[158:161], v[34:49]
	v_exp_f32_e32 v151, v74
	v_exp_f32_e32 v152, v75
	v_exp_f32_e32 v153, v76
	v_exp_f32_e32 v178, v77
	v_exp_f32_e32 v134, v78
	v_exp_f32_e32 v135, v79
	v_exp_f32_e32 v136, v80
	v_exp_f32_e32 v137, v81
	v_mfma_f32_32x32x16_bf16 v[98:113], v[130:133], v[154:157], v[98:113]
	v_exp_f32_e32 v179, v50
	v_exp_f32_e32 v185, v51
	v_exp_f32_e32 v186, v52
	v_exp_f32_e32 v187, v53
	v_exp_f32_e32 v194, v54
	v_exp_f32_e32 v195, v55
	v_exp_f32_e32 v196, v56
	v_exp_f32_e32 v197, v57
	s_waitcnt lgkmcnt(0)
	v_mfma_f32_32x32x16_bf16 v[82:97], v[138:141], v[154:157], v[82:97]
	v_exp_f32_e32 v198, v58
	v_exp_f32_e32 v199, v59
	v_exp_f32_e32 v200, v60
	v_exp_f32_e32 v201, v61
	v_exp_f32_e32 v138, v62
	v_exp_f32_e32 v139, v63
	v_exp_f32_e32 v140, v64
	v_exp_f32_e32 v141, v65
	s_cmp_gt_i32 s24, 2
	s_cselect_b32 s25, -3, 2
	s_add_i32 s25, s25, s24
	s_mulk_i32 s25, 0x2400
	v_add_u32_e32 v50, s25, v182
	s_add_i32 s25, s24, 1
	s_cmp_lg_u32 s24, 4
	s_cselect_b32 s25, s25, 0
	s_add_i32 s24, s23, -3
	s_min_u32 s26, s24, s13
	s_lshl_b32 s92, s26, 13
	s_waitcnt vmcnt(3)
	ds_write_b128 v182, v[118:121] offset:27648
	s_waitcnt vmcnt(2)
	ds_write_b128 v50, v[114:117] offset:36864
	s_add_u32 vcc_lo, s100, s92
	s_addc_u32 vcc_hi, s101, 0
	global_load_dwordx4 v[118:121], v248, vcc
	s_add_i32 s92, s23, -4
	s_lshl_b32 s92, s92, 7
	s_add_u32 vcc_lo, s98, s92
	s_addc_u32 vcc_hi, s99, 0
	global_load_dwordx4 v[114:117], v249, vcc
	s_mul_i32 s27, s25, 0x2400
	s_add_i32 s28, s27, 0xffffdc00
	s_cmp_lg_u32 s25, 0
	s_cselect_b32 s28, s28, 0x9000
	v_add_u32_e32 v78, s28, v163
	ds_read_b128 v[50:53], v78 offset:36864
	ds_read_b128 v[54:57], v78 offset:36896
	ds_read_b128 v[58:61], v78 offset:41472
	ds_read_b128 v[62:65], v78 offset:41504
	ds_read_b128 v[66:69], v78 offset:36928
	ds_read_b128 v[70:73], v78 offset:36960
	ds_read_b128 v[74:77], v78 offset:41536
	ds_read_b128 v[78:81], v78 offset:41568
	s_setprio 3
	v_cvt_pk_bf16_f32 v130, v142, v143
	v_cvt_pk_bf16_f32 v131, v144, v145
	v_cvt_pk_bf16_f32 v132, v147, v148
	v_cvt_pk_bf16_f32 v133, v149, v150
	s_waitcnt lgkmcnt(7)
	s_nop 0
	v_mfma_f32_32x32x16_bf16 v[18:33], v[50:53], v[130:133], v[18:33]
	v_add_f32_e32 v176, v142, v143
	v_add_f32_e32 v176, v176, v144
	v_add_f32_e32 v176, v176, v145
	s_waitcnt lgkmcnt(5)
	v_mfma_f32_32x32x16_bf16 v[2:17], v[58:61], v[130:133], v[2:17]
	v_cvt_pk_bf16_f32 v50, v151, v152
	v_cvt_pk_bf16_f32 v51, v153, v178
	v_cvt_pk_bf16_f32 v52, v134, v135
	v_cvt_pk_bf16_f32 v53, v136, v137
	v_add_f32_e32 v176, v176, v147
	v_add_f32_e32 v176, v176, v148
	v_add_f32_e32 v176, v176, v149
	v_add_f32_e32 v176, v176, v150
	s_nop 0
	v_mfma_f32_32x32x16_bf16 v[18:33], v[54:57], v[50:53], v[18:33]
	v_add_f32_e32 v176, v176, v151
	v_add_f32_e32 v176, v176, v152
	v_add_f32_e32 v176, v176, v153
	v_add_f32_e32 v176, v176, v178
	s_waitcnt lgkmcnt(4)
	v_mfma_f32_32x32x16_bf16 v[2:17], v[62:65], v[50:53], v[2:17]
	v_cvt_pk_bf16_f32 v54, v179, v185
	v_cvt_pk_bf16_f32 v55, v186, v187
	v_cvt_pk_bf16_f32 v56, v194, v195
	v_cvt_pk_bf16_f32 v57, v196, v197
	v_add_f32_e32 v176, v176, v134
	v_add_f32_e32 v176, v176, v135
	v_add_f32_e32 v176, v176, v136
	v_add_f32_e32 v176, v176, v137
	s_waitcnt lgkmcnt(3)
	v_mfma_f32_32x32x16_bf16 v[18:33], v[66:69], v[54:57], v[18:33]
	v_add_f32_e32 v176, v176, v179
	v_add_f32_e32 v176, v176, v185
	v_add_f32_e32 v176, v176, v186
	v_add_f32_e32 v176, v176, v187
	s_waitcnt lgkmcnt(1)
	v_mfma_f32_32x32x16_bf16 v[2:17], v[74:77], v[54:57], v[2:17]
	v_cvt_pk_bf16_f32 v50, v198, v199
	v_cvt_pk_bf16_f32 v51, v200, v201
	v_cvt_pk_bf16_f32 v52, v138, v139
	v_cvt_pk_bf16_f32 v53, v140, v141
	v_add_f32_e32 v176, v176, v194
	v_add_f32_e32 v176, v176, v195
	v_add_f32_e32 v176, v176, v196
	v_add_f32_e32 v176, v176, v197
	s_nop 0
	v_mfma_f32_32x32x16_bf16 v[18:33], v[70:73], v[50:53], v[18:33]
	v_add_f32_e32 v176, v176, v198
	v_add_f32_e32 v176, v176, v199
	v_add_f32_e32 v176, v176, v200
	v_add_f32_e32 v176, v176, v201
	s_waitcnt lgkmcnt(0)
	v_mfma_f32_32x32x16_bf16 v[2:17], v[78:81], v[50:53], v[2:17]
	v_add_f32_e32 v176, v176, v138
	v_add_f32_e32 v176, v176, v139
	v_add_f32_e32 v176, v176, v140
	v_add_f32_e32 v176, v176, v141
	s_setprio 2
	s_waitcnt lgkmcnt(0)
	s_barrier
	ds_read_b128 v[240:243], v165 offset:18432
	ds_read_b128 v[244:247], v165 offset:23040
	ds_read_b128 v[134:137], v165 offset:18464
	ds_read_b128 v[138:141], v165 offset:23072
	v_add_f32_e32 v1, v1, v146
	v_exp_f32_e32 v142, v98
	v_exp_f32_e32 v143, v99
	v_exp_f32_e32 v144, v100
	v_exp_f32_e32 v145, v101
	v_exp_f32_e32 v146, v102
	v_exp_f32_e32 v147, v103
	v_exp_f32_e32 v148, v104
	v_exp_f32_e32 v149, v105
	s_waitcnt lgkmcnt(2)
	v_mfma_f32_32x32x16_bf16 v[66:81], v[240:243], v[158:161], v[34:49]
	v_mfma_f32_32x32x16_bf16 v[50:65], v[244:247], v[158:161], v[34:49]
	v_exp_f32_e32 v150, v106
	v_exp_f32_e32 v151, v107
	v_exp_f32_e32 v152, v108
	v_exp_f32_e32 v153, v109
	v_exp_f32_e32 v177, v110
	v_exp_f32_e32 v178, v111
	v_exp_f32_e32 v179, v112
	v_exp_f32_e32 v185, v113
	s_waitcnt lgkmcnt(1)
	v_mfma_f32_32x32x16_bf16 v[66:81], v[134:137], v[154:157], v[66:81]
	v_exp_f32_e32 v186, v82
	v_exp_f32_e32 v187, v83
	v_exp_f32_e32 v194, v84
	v_exp_f32_e32 v195, v85
	v_exp_f32_e32 v134, v86
	v_exp_f32_e32 v135, v87
	v_exp_f32_e32 v136, v88
	v_exp_f32_e32 v137, v89
	s_waitcnt lgkmcnt(0)
	v_mfma_f32_32x32x16_bf16 v[50:65], v[138:141], v[154:157], v[50:65]
	v_exp_f32_e32 v196, v90
	v_exp_f32_e32 v197, v91
	v_exp_f32_e32 v198, v92
	v_exp_f32_e32 v199, v93
	v_exp_f32_e32 v138, v94
	v_exp_f32_e32 v139, v95
	v_exp_f32_e32 v140, v96
	v_exp_f32_e32 v141, v97
	s_cmp_gt_i32 s25, 2
	s_cselect_b32 s28, -3, 2
	s_waitcnt vmcnt(3)
	ds_write_b128 v182, v[126:129]
	s_add_i32 s28, s28, s25
	v_add_u32_e32 v126, s27, v163
	s_add_i32 s27, s23, -2
	s_mulk_i32 s28, 0x2400
	s_min_u32 s27, s27, s13
	v_add_u32_e32 v82, s28, v182
	s_lshl_b32 s92, s27, 13
	s_waitcnt vmcnt(2)
	ds_write_b128 v82, v[122:125] offset:36864
	ds_read_b128 v[240:243], v165 offset:27648
	ds_read_b128 v[244:247], v165 offset:32256
	ds_read_b128 v[82:85], v126 offset:41472
	ds_read_b128 v[86:89], v126 offset:36864
	ds_read_b128 v[90:93], v126 offset:36896
	ds_read_b128 v[94:97], v126 offset:41504
	ds_read_b128 v[106:109], v126 offset:36928
	ds_read_b128 v[110:113], v126 offset:41536
	ds_read_b128 v[122:125], v126 offset:36960
	ds_read_b128 v[126:129], v126 offset:41568
	s_add_u32 vcc_lo, s100, s92
	s_addc_u32 vcc_hi, s101, 0
	global_load_dwordx4 v[98:101], v248, vcc
	s_lshl_b32 s92, s26, 7
	s_add_u32 vcc_lo, s98, s92
	s_addc_u32 vcc_hi, s99, 0
	global_load_dwordx4 v[102:105], v249, vcc
	v_add_f32_e32 v1, v1, v176
	s_add_i32 s28, s25, 1
	s_setprio 1
	v_cvt_pk_bf16_f32 v130, v142, v143
	v_cvt_pk_bf16_f32 v131, v144, v145
	v_cvt_pk_bf16_f32 v132, v146, v147
	v_cvt_pk_bf16_f32 v133, v148, v149
	s_waitcnt lgkmcnt(6)
	s_nop 0
	v_mfma_f32_32x32x16_bf16 v[18:33], v[86:89], v[130:133], v[18:33]
	v_add_f32_e32 v176, v142, v143
	v_add_f32_e32 v176, v176, v144
	v_add_f32_e32 v176, v176, v145
	s_nop 0
	v_mfma_f32_32x32x16_bf16 v[2:17], v[82:85], v[130:133], v[2:17]
	v_cvt_pk_bf16_f32 v86, v150, v151
	v_cvt_pk_bf16_f32 v87, v152, v153
	v_cvt_pk_bf16_f32 v88, v177, v178
	v_cvt_pk_bf16_f32 v89, v179, v185
	v_add_f32_e32 v176, v176, v146
	v_add_f32_e32 v176, v176, v147
	v_add_f32_e32 v176, v176, v148
	v_add_f32_e32 v176, v176, v149
	s_waitcnt lgkmcnt(5)
	v_mfma_f32_32x32x16_bf16 v[18:33], v[90:93], v[86:89], v[18:33]
	v_add_f32_e32 v176, v176, v150
	v_add_f32_e32 v176, v176, v151
	v_add_f32_e32 v176, v176, v152
	v_add_f32_e32 v176, v176, v153
	s_waitcnt lgkmcnt(4)
	v_mfma_f32_32x32x16_bf16 v[2:17], v[94:97], v[86:89], v[2:17]
	v_cvt_pk_bf16_f32 v82, v186, v187
	v_cvt_pk_bf16_f32 v83, v194, v195
	v_cvt_pk_bf16_f32 v84, v134, v135
	v_cvt_pk_bf16_f32 v85, v136, v137
	v_add_f32_e32 v176, v176, v177
	v_add_f32_e32 v176, v176, v178
	v_add_f32_e32 v176, v176, v179
	v_add_f32_e32 v176, v176, v185
	s_waitcnt lgkmcnt(3)
	v_mfma_f32_32x32x16_bf16 v[18:33], v[106:109], v[82:85], v[18:33]
	v_add_f32_e32 v176, v176, v186
	v_add_f32_e32 v176, v176, v187
	v_add_f32_e32 v176, v176, v194
	v_add_f32_e32 v176, v176, v195
	s_waitcnt lgkmcnt(2)
	v_mfma_f32_32x32x16_bf16 v[2:17], v[110:113], v[82:85], v[2:17]
	v_cvt_pk_bf16_f32 v86, v196, v197
	v_cvt_pk_bf16_f32 v87, v198, v199
	v_cvt_pk_bf16_f32 v88, v138, v139
	v_cvt_pk_bf16_f32 v89, v140, v141
	v_add_f32_e32 v176, v176, v134
	v_add_f32_e32 v176, v176, v135
	v_add_f32_e32 v176, v176, v136
	v_add_f32_e32 v176, v176, v137
	s_waitcnt lgkmcnt(1)
	v_mfma_f32_32x32x16_bf16 v[18:33], v[122:125], v[86:89], v[18:33]
	v_add_f32_e32 v176, v176, v196
	v_add_f32_e32 v176, v176, v197
	v_add_f32_e32 v176, v176, v198
	v_add_f32_e32 v176, v176, v199
	s_waitcnt lgkmcnt(0)
	v_mfma_f32_32x32x16_bf16 v[2:17], v[126:129], v[86:89], v[2:17]
	v_add_f32_e32 v176, v176, v138
	v_add_f32_e32 v176, v176, v139
	v_add_f32_e32 v176, v176, v140
	v_add_f32_e32 v176, v176, v141
	s_setprio 0
	ds_read_b128 v[106:109], v165 offset:27680
	ds_read_b128 v[122:125], v165 offset:32288
	s_cmp_lg_u32 s25, 4
	s_cselect_b32 s25, s28, 0
	s_waitcnt lgkmcnt(2)
	v_mfma_f32_32x32x16_bf16 v[138:153], v[240:243], v[158:161], v[34:49]
	v_exp_f32_e32 v126, v66
	v_exp_f32_e32 v127, v67
	v_exp_f32_e32 v128, v68
	v_exp_f32_e32 v129, v69
	v_exp_f32_e32 v130, v70
	v_exp_f32_e32 v131, v71
	v_exp_f32_e32 v132, v72
	v_exp_f32_e32 v133, v73
	s_waitcnt lgkmcnt(1)
	v_mfma_f32_32x32x16_bf16 v[82:97], v[244:247], v[158:161], v[34:49]
	v_exp_f32_e32 v134, v74
	v_exp_f32_e32 v135, v75
	v_exp_f32_e32 v136, v76
	v_exp_f32_e32 v137, v77
	v_exp_f32_e32 v177, v78
	v_exp_f32_e32 v178, v79
	v_exp_f32_e32 v179, v80
	v_exp_f32_e32 v185, v81
	v_mfma_f32_32x32x16_bf16 v[138:153], v[106:109], v[154:157], v[138:153]
	v_exp_f32_e32 v80, v50
	v_exp_f32_e32 v81, v51
	v_exp_f32_e32 v186, v52
	v_exp_f32_e32 v187, v53
	v_exp_f32_e32 v194, v54
	v_exp_f32_e32 v195, v55
	v_exp_f32_e32 v196, v56
	v_exp_f32_e32 v197, v57
	s_waitcnt lgkmcnt(0)
	v_mfma_f32_32x32x16_bf16 v[82:97], v[122:125], v[154:157], v[82:97]
	v_exp_f32_e32 v198, v58
	v_exp_f32_e32 v199, v59
	v_exp_f32_e32 v200, v60
	v_exp_f32_e32 v201, v61
	v_exp_f32_e32 v122, v62
	v_exp_f32_e32 v123, v63
	v_exp_f32_e32 v124, v64
	v_exp_f32_e32 v125, v65
	s_cmp_gt_i32 s25, 2
	s_cselect_b32 s26, -3, 2
	s_add_i32 s26, s26, s25
	s_mulk_i32 s26, 0x2400
	v_add_u32_e32 v50, s26, v182
	s_add_i32 s26, s25, 1
	s_cmp_lg_u32 s25, 4
	s_cselect_b32 s25, s26, 0
	s_add_i32 s26, s23, -1
	s_min_u32 s26, s26, s13
	s_lshl_b32 s92, s26, 13
	s_waitcnt vmcnt(3)
	ds_write_b128 v182, v[118:121] offset:9216
	s_waitcnt vmcnt(2)
	ds_write_b128 v50, v[114:117] offset:36864
	s_add_u32 vcc_lo, s100, s92
	s_addc_u32 vcc_hi, s101, 0
	global_load_dwordx4 v[56:59], v248, vcc
	s_lshl_b32 s92, s27, 7
	s_add_u32 vcc_lo, s98, s92
	s_addc_u32 vcc_hi, s99, 0
	global_load_dwordx4 v[52:55], v249, vcc
	s_nop 0
	s_mul_i32 s27, s25, 0x2400
	s_add_i32 s28, s27, 0xffffdc00
	s_cmp_lg_u32 s25, 0
	s_cselect_b32 s28, s28, 0x9000
	v_add_u32_e32 v50, s28, v163
	ds_read_b128 v[60:63], v50 offset:36864
	ds_read_b128 v[64:67], v50 offset:36896
	ds_read_b128 v[68:71], v50 offset:41472
	ds_read_b128 v[72:75], v50 offset:41504
	ds_read_b128 v[76:79], v50 offset:36928
	ds_read_b128 v[106:109], v50 offset:36960
	ds_read_b128 v[110:113], v50 offset:41536
	ds_read_b128 v[114:117], v50 offset:41568
	s_setprio 3
	v_cvt_pk_bf16_f32 v118, v126, v127
	v_cvt_pk_bf16_f32 v119, v128, v129
	v_cvt_pk_bf16_f32 v120, v130, v131
	v_cvt_pk_bf16_f32 v121, v132, v133
	s_waitcnt lgkmcnt(7)
	s_nop 0
	v_mfma_f32_32x32x16_bf16 v[18:33], v[60:63], v[118:121], v[18:33]
	v_add_f32_e32 v50, v126, v127
	v_add_f32_e32 v50, v50, v128
	v_add_f32_e32 v50, v50, v129
	s_waitcnt lgkmcnt(5)
	v_mfma_f32_32x32x16_bf16 v[2:17], v[68:71], v[118:121], v[2:17]
	v_cvt_pk_bf16_f32 v60, v134, v135
	v_cvt_pk_bf16_f32 v61, v136, v137
	v_cvt_pk_bf16_f32 v62, v177, v178
	v_cvt_pk_bf16_f32 v63, v179, v185
	v_add_f32_e32 v50, v50, v130
	v_add_f32_e32 v50, v50, v131
	v_add_f32_e32 v50, v50, v132
	v_add_f32_e32 v50, v50, v133
	s_nop 0
	v_mfma_f32_32x32x16_bf16 v[18:33], v[64:67], v[60:63], v[18:33]
	v_add_f32_e32 v50, v50, v134
	v_add_f32_e32 v50, v50, v135
	v_add_f32_e32 v50, v50, v136
	v_add_f32_e32 v50, v50, v137
	s_waitcnt lgkmcnt(4)
	v_mfma_f32_32x32x16_bf16 v[2:17], v[72:75], v[60:63], v[2:17]
	v_cvt_pk_bf16_f32 v64, v80, v81
	v_cvt_pk_bf16_f32 v65, v186, v187
	v_cvt_pk_bf16_f32 v66, v194, v195
	v_cvt_pk_bf16_f32 v67, v196, v197
	v_add_f32_e32 v50, v50, v177
	v_add_f32_e32 v50, v50, v178
	v_add_f32_e32 v50, v50, v179
	v_add_f32_e32 v50, v50, v185
	s_waitcnt lgkmcnt(3)
	v_mfma_f32_32x32x16_bf16 v[18:33], v[76:79], v[64:67], v[18:33]
	v_add_f32_e32 v50, v50, v80
	v_add_f32_e32 v50, v50, v81
	v_add_f32_e32 v50, v50, v186
	v_add_f32_e32 v50, v50, v187
	s_waitcnt lgkmcnt(1)
	v_mfma_f32_32x32x16_bf16 v[2:17], v[110:113], v[64:67], v[2:17]
	v_cvt_pk_bf16_f32 v60, v198, v199
	v_cvt_pk_bf16_f32 v61, v200, v201
	v_cvt_pk_bf16_f32 v62, v122, v123
	v_cvt_pk_bf16_f32 v63, v124, v125
	v_add_f32_e32 v50, v50, v194
	v_add_f32_e32 v50, v50, v195
	v_add_f32_e32 v50, v50, v196
	v_add_f32_e32 v50, v50, v197
	s_nop 0
	v_mfma_f32_32x32x16_bf16 v[18:33], v[106:109], v[60:63], v[18:33]
	v_add_f32_e32 v50, v50, v198
	v_add_f32_e32 v50, v50, v199
	v_add_f32_e32 v50, v50, v200
	v_add_f32_e32 v50, v50, v201
	s_waitcnt lgkmcnt(0)
	v_mfma_f32_32x32x16_bf16 v[2:17], v[114:117], v[60:63], v[2:17]
	v_add_f32_e32 v50, v50, v122
	v_add_f32_e32 v50, v50, v123
	v_add_f32_e32 v50, v50, v124
	v_add_f32_e32 v50, v50, v125
	s_setprio 2
	s_waitcnt lgkmcnt(0)
	s_barrier
	ds_read_b128 v[240:243], v165
	ds_read_b128 v[244:247], v165 offset:4608
	ds_read_b128 v[68:71], v165 offset:32
	ds_read_b128 v[72:75], v165 offset:4640
	v_add_f32_e32 v1, v1, v176
	v_exp_f32_e32 v176, v138
	v_exp_f32_e32 v177, v139
	v_exp_f32_e32 v178, v140
	v_exp_f32_e32 v179, v141
	v_exp_f32_e32 v185, v142
	v_exp_f32_e32 v186, v143
	v_exp_f32_e32 v187, v144
	v_exp_f32_e32 v194, v145
	s_waitcnt lgkmcnt(2)
	v_mfma_f32_32x32x16_bf16 v[122:137], v[240:243], v[158:161], v[34:49]
	v_mfma_f32_32x32x16_bf16 v[106:121], v[244:247], v[158:161], v[34:49]
	v_exp_f32_e32 v195, v146
	v_exp_f32_e32 v196, v147
	v_exp_f32_e32 v197, v148
	v_exp_f32_e32 v198, v149
	v_exp_f32_e32 v146, v150
	v_exp_f32_e32 v147, v151
	v_exp_f32_e32 v148, v152
	v_exp_f32_e32 v149, v153
	s_waitcnt lgkmcnt(1)
	v_mfma_f32_32x32x16_bf16 v[122:137], v[68:71], v[154:157], v[122:137]
	v_exp_f32_e32 v150, v82
	v_exp_f32_e32 v151, v83
	v_exp_f32_e32 v152, v84
	v_exp_f32_e32 v153, v85
	v_exp_f32_e32 v199, v86
	v_exp_f32_e32 v200, v87
	v_exp_f32_e32 v201, v88
	v_exp_f32_e32 v202, v89
	s_waitcnt lgkmcnt(0)
	v_mfma_f32_32x32x16_bf16 v[106:121], v[72:75], v[154:157], v[106:121]
	v_exp_f32_e32 v203, v90
	v_exp_f32_e32 v204, v91
	v_exp_f32_e32 v205, v92
	v_exp_f32_e32 v206, v93
	v_exp_f32_e32 v207, v94
	v_exp_f32_e32 v208, v95
	v_exp_f32_e32 v209, v96
	v_exp_f32_e32 v210, v97
	v_add_u32_e32 v88, s27, v163
	ds_read_b128 v[240:243], v165 offset:9216
	ds_read_b128 v[244:247], v165 offset:13824
	ds_read_b128 v[60:63], v88 offset:41472
	ds_read_b128 v[64:67], v88 offset:36864
	ds_read_b128 v[68:71], v88 offset:36896
	ds_read_b128 v[72:75], v88 offset:41504
	ds_read_b128 v[76:79], v88 offset:36928
	ds_read_b128 v[80:83], v88 offset:41536
	ds_read_b128 v[84:87], v88 offset:36960
	ds_read_b128 v[88:91], v88 offset:41568
	s_cmp_gt_i32 s25, 2
	s_cselect_b32 s28, -3, 2
	s_add_i32 s28, s28, s25
	s_mulk_i32 s28, 0x2400
	s_min_u32 s27, s23, s13
	v_add_u32_e32 v51, s28, v182
	s_lshl_b32 s92, s27, 13
	s_waitcnt vmcnt(3)
	ds_write_b128 v182, v[98:101] offset:18432
	s_waitcnt vmcnt(2)
	ds_write_b128 v51, v[102:105] offset:36864
	v_add_f32_e32 v1, v1, v50
	s_add_u32 vcc_lo, s100, s92
	s_addc_u32 vcc_hi, s101, 0
	global_load_dwordx4 v[138:141], v248, vcc
	s_lshl_b32 s92, s26, 7
	s_add_u32 vcc_lo, s98, s92
	s_addc_u32 vcc_hi, s99, 0
	global_load_dwordx4 v[142:145], v249, vcc
	s_setprio 1
	v_mov_b32_e32 v51, v122
	v_cvt_pk_bf16_f32 v92, v176, v177
	v_cvt_pk_bf16_f32 v93, v178, v179
	v_cvt_pk_bf16_f32 v94, v185, v186
	v_cvt_pk_bf16_f32 v95, v187, v194
	s_waitcnt lgkmcnt(8)
	s_nop 0
	v_mfma_f32_32x32x16_bf16 v[18:33], v[64:67], v[92:95], v[18:33]
	v_max3_f32 v51, v51, v123, v124
	v_max3_f32 v51, v51, v125, v126
	v_add_f32_e32 v50, v176, v177
	v_add_f32_e32 v50, v50, v178
	v_add_f32_e32 v50, v50, v179
	s_nop 0
	v_mfma_f32_32x32x16_bf16 v[2:17], v[60:63], v[92:95], v[2:17]
	v_cvt_pk_bf16_f32 v64, v195, v196
	v_cvt_pk_bf16_f32 v65, v197, v198
	v_cvt_pk_bf16_f32 v66, v146, v147
	v_cvt_pk_bf16_f32 v67, v148, v149
	v_max3_f32 v51, v51, v127, v128
	v_max3_f32 v51, v51, v129, v130
	v_add_f32_e32 v50, v50, v185
	v_add_f32_e32 v50, v50, v186
	v_add_f32_e32 v50, v50, v187
	v_add_f32_e32 v50, v50, v194
	s_waitcnt lgkmcnt(7)
	v_mfma_f32_32x32x16_bf16 v[18:33], v[68:71], v[64:67], v[18:33]
	v_max3_f32 v51, v51, v131, v132
	v_max3_f32 v51, v51, v133, v134
	v_add_f32_e32 v50, v50, v195
	v_add_f32_e32 v50, v50, v196
	v_add_f32_e32 v50, v50, v197
	v_add_f32_e32 v50, v50, v198
	s_waitcnt lgkmcnt(6)
	v_mfma_f32_32x32x16_bf16 v[2:17], v[72:75], v[64:67], v[2:17]
	v_cvt_pk_bf16_f32 v60, v150, v151
	v_cvt_pk_bf16_f32 v61, v152, v153
	v_cvt_pk_bf16_f32 v62, v199, v200
	v_cvt_pk_bf16_f32 v63, v201, v202
	v_max3_f32 v51, v51, v135, v136
	v_max3_f32 v51, v51, v137, v106
	v_add_f32_e32 v50, v50, v146
	v_add_f32_e32 v50, v50, v147
	v_add_f32_e32 v50, v50, v148
	v_add_f32_e32 v50, v50, v149
	s_waitcnt lgkmcnt(5)
	v_mfma_f32_32x32x16_bf16 v[18:33], v[76:79], v[60:63], v[18:33]
	v_max3_f32 v51, v51, v107, v108
	v_max3_f32 v51, v51, v109, v110
	v_add_f32_e32 v50, v50, v150
	v_add_f32_e32 v50, v50, v151
	v_add_f32_e32 v50, v50, v152
	v_add_f32_e32 v50, v50, v153
	s_waitcnt lgkmcnt(4)
	v_mfma_f32_32x32x16_bf16 v[2:17], v[80:83], v[60:63], v[2:17]
	v_cvt_pk_bf16_f32 v64, v203, v204
	v_cvt_pk_bf16_f32 v65, v205, v206
	v_cvt_pk_bf16_f32 v66, v207, v208
	v_cvt_pk_bf16_f32 v67, v209, v210
	v_max3_f32 v51, v51, v111, v112
	v_max3_f32 v51, v51, v113, v114
	v_add_f32_e32 v50, v50, v199
	v_add_f32_e32 v50, v50, v200
	v_add_f32_e32 v50, v50, v201
	v_add_f32_e32 v50, v50, v202
	s_waitcnt lgkmcnt(3)
	v_mfma_f32_32x32x16_bf16 v[18:33], v[84:87], v[64:67], v[18:33]
	v_max3_f32 v51, v51, v115, v116
	v_max3_f32 v51, v51, v117, v118
	v_add_f32_e32 v50, v50, v203
	v_add_f32_e32 v50, v50, v204
	v_add_f32_e32 v50, v50, v205
	v_add_f32_e32 v50, v50, v206
	s_waitcnt lgkmcnt(2)
	v_mfma_f32_32x32x16_bf16 v[2:17], v[88:91], v[64:67], v[2:17]
	v_max3_f32 v51, v51, v119, v120
	v_max3_f32 v51, v51, v121, v121
	v_add_f32_e32 v50, v50, v207
	v_add_f32_e32 v50, v50, v208
	v_add_f32_e32 v50, v50, v209
	v_add_f32_e32 v50, v50, v210
	s_setprio 0
	ds_read_b128 v[146:149], v165 offset:9248
	ds_read_b128 v[60:63], v165 offset:13856
	v_add_f32_e32 v50, v1, v50
	v_mov_b32_e32 v1, v51
	s_nop 1
	v_permlane32_swap_b32_e32 v51, v1
	v_max_f32_e32 v1, v51, v1
	v_cmp_lt_f32_e32 vcc, s52, v1
	s_cbranch_vccz .LBB0_643
	v_max_f32_e32 v1, v1, v1
	v_max_f32_e32 v68, 0, v1
	v_add_f32_e32 v183, v183, v68
	v_xor_b32_e32 v34, 0x80000000, v183
	v_pk_add_f32 v[122:123], v[122:123], v[68:69] op_sel_hi:[1,0] neg_lo:[0,1] neg_hi:[0,1]
	v_pk_add_f32 v[106:107], v[106:107], v[68:69] op_sel_hi:[1,0] neg_lo:[0,1] neg_hi:[0,1]
	v_pk_add_f32 v[124:125], v[124:125], v[68:69] op_sel_hi:[1,0] neg_lo:[0,1] neg_hi:[0,1]
	v_pk_add_f32 v[108:109], v[108:109], v[68:69] op_sel_hi:[1,0] neg_lo:[0,1] neg_hi:[0,1]
	v_pk_add_f32 v[126:127], v[126:127], v[68:69] op_sel_hi:[1,0] neg_lo:[0,1] neg_hi:[0,1]
	v_pk_add_f32 v[110:111], v[110:111], v[68:69] op_sel_hi:[1,0] neg_lo:[0,1] neg_hi:[0,1]
	v_pk_add_f32 v[128:129], v[128:129], v[68:69] op_sel_hi:[1,0] neg_lo:[0,1] neg_hi:[0,1]
	v_pk_add_f32 v[112:113], v[112:113], v[68:69] op_sel_hi:[1,0] neg_lo:[0,1] neg_hi:[0,1]
	v_pk_add_f32 v[130:131], v[130:131], v[68:69] op_sel_hi:[1,0] neg_lo:[0,1] neg_hi:[0,1]
	v_pk_add_f32 v[114:115], v[114:115], v[68:69] op_sel_hi:[1,0] neg_lo:[0,1] neg_hi:[0,1]
	v_pk_add_f32 v[132:133], v[132:133], v[68:69] op_sel_hi:[1,0] neg_lo:[0,1] neg_hi:[0,1]
	v_pk_add_f32 v[116:117], v[116:117], v[68:69] op_sel_hi:[1,0] neg_lo:[0,1] neg_hi:[0,1]
	v_pk_add_f32 v[134:135], v[134:135], v[68:69] op_sel_hi:[1,0] neg_lo:[0,1] neg_hi:[0,1]
	v_pk_add_f32 v[118:119], v[118:119], v[68:69] op_sel_hi:[1,0] neg_lo:[0,1] neg_hi:[0,1]
	v_pk_add_f32 v[136:137], v[136:137], v[68:69] op_sel_hi:[1,0] neg_lo:[0,1] neg_hi:[0,1]
	v_pk_add_f32 v[120:121], v[120:121], v[68:69] op_sel_hi:[1,0] neg_lo:[0,1] neg_hi:[0,1]
	v_exp_f32_e64 v68, -v68
	v_mov_b32_e32 v35, v34
	v_mov_b32_e32 v36, v34
	v_mov_b32_e32 v37, v34
	v_mov_b32_e32 v38, v34
	v_mov_b32_e32 v39, v34
	v_mov_b32_e32 v40, v34
	v_mov_b32_e32 v41, v34
	v_mov_b32_e32 v42, v34
	v_mov_b32_e32 v43, v34
	v_mov_b32_e32 v44, v34
	v_mov_b32_e32 v45, v34
	v_mov_b32_e32 v46, v34
	v_mov_b32_e32 v47, v34
	v_mov_b32_e32 v48, v34
	v_mov_b32_e32 v49, v34
	s_nop 11
	v_pk_mul_f32 v[32:33], v[32:33], v[68:69] op_sel_hi:[1,0]
	v_pk_mul_f32 v[30:31], v[30:31], v[68:69] op_sel_hi:[1,0]
	v_pk_mul_f32 v[28:29], v[28:29], v[68:69] op_sel_hi:[1,0]
	v_pk_mul_f32 v[26:27], v[26:27], v[68:69] op_sel_hi:[1,0]
	v_pk_mul_f32 v[24:25], v[24:25], v[68:69] op_sel_hi:[1,0]
	v_pk_mul_f32 v[22:23], v[22:23], v[68:69] op_sel_hi:[1,0]
	v_pk_mul_f32 v[20:21], v[20:21], v[68:69] op_sel_hi:[1,0]
	v_pk_mul_f32 v[18:19], v[18:19], v[68:69] op_sel_hi:[1,0]
	v_pk_mul_f32 v[16:17], v[16:17], v[68:69] op_sel_hi:[1,0]
	v_pk_mul_f32 v[14:15], v[14:15], v[68:69] op_sel_hi:[1,0]
	v_pk_mul_f32 v[12:13], v[12:13], v[68:69] op_sel_hi:[1,0]
	v_pk_mul_f32 v[10:11], v[10:11], v[68:69] op_sel_hi:[1,0]
	v_pk_mul_f32 v[8:9], v[8:9], v[68:69] op_sel_hi:[1,0]
	v_pk_mul_f32 v[6:7], v[6:7], v[68:69] op_sel_hi:[1,0]
	v_pk_mul_f32 v[4:5], v[4:5], v[68:69] op_sel_hi:[1,0]
	v_pk_mul_f32 v[2:3], v[2:3], v[68:69] op_sel_hi:[1,0]
	v_mul_f32_e32 v50, v50, v68
.LBB0_643:
	s_add_i32 s26, s25, 1
	s_cmp_lg_u32 s25, 4
	s_cselect_b32 s25, s26, 0
	s_waitcnt lgkmcnt(2)
	v_mfma_f32_32x32x16_bf16 v[82:97], v[240:243], v[158:161], v[34:49]
	v_exp_f32_e32 v102, v122
	v_exp_f32_e32 v103, v123
	v_exp_f32_e32 v104, v124
	v_exp_f32_e32 v105, v125
	v_exp_f32_e32 v98, v126
	v_exp_f32_e32 v99, v127
	v_exp_f32_e32 v100, v128
	v_exp_f32_e32 v101, v129
	s_waitcnt lgkmcnt(1)
	v_mfma_f32_32x32x16_bf16 v[66:81], v[244:247], v[158:161], v[34:49]
	v_exp_f32_e32 v194, v130
	v_exp_f32_e32 v187, v131
	v_exp_f32_e32 v186, v132
	v_exp_f32_e32 v185, v133
	v_exp_f32_e32 v133, v134
	v_exp_f32_e32 v132, v135
	v_exp_f32_e32 v131, v136
	v_exp_f32_e32 v130, v137
	v_mfma_f32_32x32x16_bf16 v[82:97], v[146:149], v[154:157], v[82:97]
	v_exp_f32_e32 v129, v106
	v_exp_f32_e32 v128, v107
	v_exp_f32_e32 v127, v108
	v_exp_f32_e32 v126, v109
	v_exp_f32_e32 v125, v110
	v_exp_f32_e32 v124, v111
	v_exp_f32_e32 v123, v112
	v_exp_f32_e32 v122, v113
	s_waitcnt lgkmcnt(0)
	v_mfma_f32_32x32x16_bf16 v[66:81], v[60:63], v[154:157], v[66:81]
	v_exp_f32_e32 v109, v114
	v_exp_f32_e32 v108, v115
	v_exp_f32_e32 v107, v116
	v_exp_f32_e32 v106, v117
	v_exp_f32_e32 v113, v118
	v_exp_f32_e32 v112, v119
	v_exp_f32_e32 v111, v120
	v_exp_f32_e32 v110, v121
	s_cmp_gt_i32 s25, 2
	s_cselect_b32 s26, -3, 2
	s_add_i32 s26, s26, s25
	s_mulk_i32 s26, 0x2400
	v_add_u32_e32 v1, s26, v182
	s_add_i32 s26, s25, 1
	s_cmp_lg_u32 s25, 4
	s_cselect_b32 s25, s26, 0
	s_add_i32 s26, s23, 8
	s_add_i32 s23, s23, 4
	s_cmp_ge_u32 s23, s2
	s_waitcnt vmcnt(3)
	ds_write_b128 v182, v[56:59] offset:27648
	s_waitcnt vmcnt(2)
	ds_write_b128 v1, v[52:55] offset:36864
	s_cbranch_scc0 .Lle_a0_cont
	s_branch .LBB0_666

.LBB0_658:
	s_lshl_b32 s1, s0, 1
	s_xor_b64 s[26:27], s[12:13], -1
	s_lshl_b32 s63, s73, 7
	s_add_i32 s19, s1, s74
	s_lshl_b32 s23, s74, 1
	s_lshl_b32 s24, s0, 2
	s_ashr_i32 s22, s63, 31
	s_mul_hi_u32 s18, s19, 0x208000
	s_mul_i32 s19, s19, 0x208000
	s_mov_b64 s[12:13], -1
	s_and_b64 vcc, exec, s[26:27]
	s_cbranch_vccz .LBB0_694
	v_mov_b32_e32 v76, v222
	v_mov_b32_e32 v53, v0
	v_readfirstlane_b32 s1, v76
	s_ashr_i32 s25, s1, 8
	s_add_i32 s25, s25, s23
	s_lshr_b32 s1, s1, 1
	s_add_i32 s2, s25, s24
	s_and_b32 s1, s1, 0x60
	s_mul_hi_i32 s12, s2, 0x4100
	s_mulk_i32 s2, 0x4100
	s_add_u32 s2, s2, s63
	v_and_b32_e32 v207, 31, v76
	s_addc_u32 s12, s12, s22
	s_or_b32 s2, s2, s1
	v_or_b32_e32 v2, s2, v207
	v_mov_b32_e32 v3, s12
	v_bfe_u32 v206, v76, 5, 1
	v_lshlrev_b64 v[2:3], 7, v[2:3]
	v_lshl_add_u64 v[2:3], s[14:15], 0, v[2:3]
	v_lshlrev_b32_e32 v52, 4, v206
	s_add_u32 s12, s40, s19
	v_lshl_add_u64 v[2:3], v[2:3], 0, v[52:53]
	s_addc_u32 s13, s41, s18
	v_ashrrev_i32_e32 v74, 3, v76
	global_load_dwordx4 v[180:183], v[2:3], off
	global_load_dwordx4 v[176:179], v[2:3], off offset:32
	global_load_dwordx4 v[172:175], v[2:3], off offset:64
	global_load_dwordx4 v[168:171], v[2:3], off offset:96
	s_add_u32 s26, s38, s19
	v_ashrrev_i32_e32 v75, 31, v74
	v_mov_b64_e32 v[2:3], s[12:13]
	v_lshlrev_b32_e32 v1, 4, v76
	s_addc_u32 s27, s39, s18
	v_lshlrev_b64 v[72:73], 7, v[74:75]
	v_mad_i64_i32 v[2:3], s[12:13], v74, s55, v[2:3]
	v_and_b32_e32 v54, 0x70, v1
	v_mov_b32_e32 v55, v0
	v_lshl_add_u64 v[196:197], v[2:3], 0, v[54:55]
	v_lshl_add_u64 v[2:3], s[26:27], 0, v[72:73]
	v_lshl_add_u64 v[198:199], v[2:3], 0, v[54:55]
	s_nop 1
	v_readfirstlane_b32 s100, v198
	v_readfirstlane_b32 s101, v199
	v_readfirstlane_b32 s98, v196
	v_readfirstlane_b32 s99, v197
	s_nop 1
	v_subrev_u32_e32 v248, s100, v198
	v_subrev_u32_e32 v249, s98, v196
	v_add_co_u32_e32 v44, vcc, s3, v198
	v_mov_b32_e32 v14, v0
	v_mov_b32_e32 v15, v0
	v_addc_co_u32_e32 v45, vcc, 0, v199, vcc
	v_mov_b32_e32 v1, v0
	v_mov_b32_e32 v2, v0
	v_mov_b32_e32 v3, v0
	v_mov_b32_e32 v4, v0
	v_mov_b32_e32 v5, v0
	v_mov_b32_e32 v6, v0
	v_mov_b32_e32 v7, v0
	v_mov_b32_e32 v8, v0
	v_mov_b32_e32 v9, v0
	v_mov_b32_e32 v10, v0
	v_mov_b32_e32 v11, v0
	v_mov_b32_e32 v12, v0
	v_mov_b32_e32 v13, v0
	v_mov_b64_e32 v[30:31], v[14:15]
	v_add_co_u32_e32 v48, vcc, s59, v198
	v_mov_b64_e32 v[28:29], v[12:13]
	v_mov_b64_e32 v[26:27], v[10:11]
	v_mov_b64_e32 v[24:25], v[8:9]
	v_mov_b64_e32 v[22:23], v[6:7]
	v_mov_b64_e32 v[20:21], v[4:5]
	v_mov_b64_e32 v[18:19], v[2:3]
	v_mov_b64_e32 v[16:17], v[0:1]
	v_addc_co_u32_e32 v49, vcc, 0, v199, vcc
	global_load_dwordx4 v[32:35], v[198:199], off
	global_load_dwordx4 v[36:39], v[196:197], off
	global_load_dwordx4 v[40:43], v[196:197], off offset:128
	s_nop 0
	global_load_dwordx4 v[44:47], v[44:45], off
	s_nop 0
	global_load_dwordx4 v[48:51], v[48:49], off
	v_mul_u32_u24_e32 v53, 0x90, v207
	v_mad_u64_u32 v[194:195], s[12:13], v74, s60, v[54:55]
	v_add3_u32 v195, 0, v53, v52
	v_add_co_u32_e32 v52, vcc, s33, v198
	v_add_u32_e32 v208, 0, v194
	s_nop 0
	v_addc_co_u32_e32 v53, vcc, 0, v199, vcc
	global_load_dwordx4 v[64:67], v[196:197], off offset:256
	global_load_dwordx4 v[68:71], v[52:53], off
	s_cmp_gt_i32 s73, 1
	s_cselect_b32 s92, 0x8000, s33
	s_cselect_b32 s2, 0x104, 4
	s_mov_b32 s27, 1
	s_add_i32 s12, s2, -1
	s_cmp_lt_i32 s73, 2
	s_barrier
	s_waitcnt vmcnt(5)
	ds_write_b128 v208, v[36:39] offset:36864
	s_waitcnt vmcnt(4)
	ds_write_b128 v208, v[40:43] offset:46080
	ds_write_b128 v208, v[32:35]
	s_waitcnt vmcnt(3)
	ds_write_b128 v208, v[44:47] offset:9216
	s_waitcnt vmcnt(2)
	ds_write_b128 v208, v[48:51] offset:18432
	s_waitcnt lgkmcnt(0)
	s_barrier
	ds_read_b128 v[48:51], v195
	ds_read_b128 v[52:55], v195 offset:4608
	s_waitcnt lgkmcnt(1)
	v_mfma_f32_32x32x16_bf16 v[32:47], v[48:51], v[180:183], v[16:31]
	v_lshl_add_u64 v[48:49], v[198:199], 0, s[92:93]
	global_load_dwordx4 v[152:155], v[48:49], off
	global_load_dwordx4 v[156:159], v[196:197], off offset:384
	ds_read_b128 v[48:51], v195 offset:32
	s_waitcnt lgkmcnt(0)
	v_mfma_f32_32x32x16_bf16 v[32:47], v[48:51], v[176:179], v[32:47]
	ds_read_b128 v[48:51], v195 offset:4640
	v_mfma_f32_32x32x16_bf16 v[16:31], v[52:55], v[180:183], v[16:31]
	s_waitcnt lgkmcnt(0)
	v_mfma_f32_32x32x16_bf16 v[16:31], v[48:51], v[176:179], v[16:31]
	ds_read_b128 v[48:51], v195 offset:64
	s_waitcnt lgkmcnt(0)
	v_mfma_f32_32x32x16_bf16 v[32:47], v[48:51], v[172:175], v[32:47]
	ds_read_b128 v[48:51], v195 offset:4672
	s_waitcnt lgkmcnt(0)
	v_mfma_f32_32x32x16_bf16 v[16:31], v[48:51], v[172:175], v[16:31]
	ds_read_b128 v[48:51], v195 offset:96
	s_waitcnt lgkmcnt(0)
	v_mfma_f32_32x32x16_bf16 v[32:47], v[48:51], v[168:171], v[32:47]
	ds_read_b128 v[48:51], v195 offset:4704
	s_waitcnt lgkmcnt(0)
	v_mfma_f32_32x32x16_bf16 v[16:31], v[48:51], v[168:171], v[16:31]
	v_max3_f32 v48, v32, v33, v34
	s_nop 0
	v_max3_f32 v48, v48, v35, v36
	s_nop 0
	v_max3_f32 v48, v48, v37, v38
	s_nop 0
	v_max3_f32 v48, v48, v39, v40
	s_nop 0
	v_max3_f32 v48, v48, v41, v42
	s_nop 0
	v_max3_f32 v48, v48, v43, v44
	s_nop 0
	v_max3_f32 v48, v48, v45, v46
	s_nop 0
	v_max3_f32 v48, v48, v47, v16
	s_nop 0
	v_max3_f32 v48, v48, v17, v18
	s_nop 0
	v_max3_f32 v48, v48, v19, v20
	s_nop 0
	v_max3_f32 v48, v48, v21, v22
	s_nop 0
	v_max3_f32 v48, v48, v23, v24
	s_nop 0
	v_max3_f32 v48, v48, v25, v26
	s_nop 0
	v_max3_f32 v48, v48, v27, v28
	s_nop 0
	v_max3_f32 v48, v48, v29, v30
	s_nop 0
	v_max3_f32 v48, v48, v31, v31
	s_setprio 0
	ds_read_b128 v[78:81], v195 offset:9216
	ds_read_b128 v[120:123], v195 offset:9248
	ds_read_b128 v[124:127], v195 offset:13824
	ds_read_b128 v[128:131], v195 offset:13856
	ds_read_b128 v[132:135], v195 offset:9280
	ds_read_b128 v[148:151], v195 offset:9312
	ds_read_b128 v[160:163], v195 offset:13888
	ds_read_b128 v[164:167], v195 offset:13920
	v_mov_b32_e32 v49, v48
	s_nop 1
	v_permlane32_swap_b32_e32 v48, v49
	v_max_f32_e32 v49, v49, v49
	v_max_f32_e32 v48, v48, v48
	v_max_f32_e32 v49, v48, v49
	v_add_f32_e32 v209, 0, v49
	v_xor_b32_e32 v48, 0x80000000, v209
	v_sub_f32_e32 v32, v32, v49
	v_sub_f32_e32 v16, v16, v49
	v_sub_f32_e32 v33, v33, v49
	v_sub_f32_e32 v17, v17, v49
	v_sub_f32_e32 v34, v34, v49
	v_sub_f32_e32 v18, v18, v49
	v_sub_f32_e32 v35, v35, v49
	v_sub_f32_e32 v19, v19, v49
	v_sub_f32_e32 v36, v36, v49
	v_sub_f32_e32 v20, v20, v49
	v_sub_f32_e32 v37, v37, v49
	v_sub_f32_e32 v21, v21, v49
	v_sub_f32_e32 v38, v38, v49
	v_sub_f32_e32 v22, v22, v49
	v_sub_f32_e32 v39, v39, v49
	v_sub_f32_e32 v23, v23, v49
	v_sub_f32_e32 v40, v40, v49
	v_sub_f32_e32 v24, v24, v49
	v_sub_f32_e32 v41, v41, v49
	v_sub_f32_e32 v25, v25, v49
	v_sub_f32_e32 v42, v42, v49
	v_sub_f32_e32 v26, v26, v49
	v_sub_f32_e32 v43, v43, v49
	v_sub_f32_e32 v27, v27, v49
	v_sub_f32_e32 v44, v44, v49
	v_sub_f32_e32 v28, v28, v49
	v_sub_f32_e32 v45, v45, v49
	v_sub_f32_e32 v29, v29, v49
	v_sub_f32_e32 v46, v46, v49
	v_sub_f32_e32 v30, v30, v49
	v_sub_f32_e32 v47, v47, v49
	v_sub_f32_e32 v31, v31, v49
	v_mov_b32_e32 v49, v48
	v_mov_b32_e32 v50, v48
	v_mov_b32_e32 v51, v48
	v_mov_b32_e32 v52, v48
	v_mov_b32_e32 v53, v48
	v_mov_b32_e32 v54, v48
	v_mov_b32_e32 v55, v48
	v_mov_b32_e32 v56, v48
	v_mov_b32_e32 v57, v48
	v_mov_b32_e32 v58, v48
	v_mov_b32_e32 v59, v48
	v_mov_b32_e32 v60, v48
	v_mov_b32_e32 v61, v48
	v_mov_b32_e32 v62, v48
	v_mov_b32_e32 v63, v48
	s_waitcnt lgkmcnt(7)
	s_nop 4
	v_mfma_f32_32x32x16_bf16 v[96:111], v[78:81], v[180:183], v[48:63]
	v_exp_f32_e32 v116, v32
	v_exp_f32_e32 v117, v33
	v_exp_f32_e32 v118, v34
	v_exp_f32_e32 v119, v35
	s_nop 0
	s_waitcnt lgkmcnt(5)
	s_nop 4
	v_mfma_f32_32x32x16_bf16 v[80:95], v[124:127], v[180:183], v[48:63]
	v_exp_f32_e32 v112, v36
	v_exp_f32_e32 v113, v37
	v_exp_f32_e32 v114, v38
	v_exp_f32_e32 v115, v39
	s_nop 0
	v_mfma_f32_32x32x16_bf16 v[96:111], v[120:123], v[176:179], v[96:111]
	v_exp_f32_e32 v187, v40
	v_exp_f32_e32 v186, v41
	v_exp_f32_e32 v185, v42
	v_exp_f32_e32 v184, v43
	s_nop 0
	s_waitcnt lgkmcnt(4)
	v_mfma_f32_32x32x16_bf16 v[80:95], v[128:131], v[176:179], v[80:95]
	v_exp_f32_e32 v147, v44
	v_exp_f32_e32 v146, v45
	v_exp_f32_e32 v145, v46
	v_exp_f32_e32 v144, v47
	s_nop 0
	s_waitcnt lgkmcnt(3)
	v_mfma_f32_32x32x16_bf16 v[96:111], v[132:135], v[172:175], v[96:111]
	v_exp_f32_e32 v143, v16
	v_exp_f32_e32 v142, v17
	v_exp_f32_e32 v141, v18
	v_exp_f32_e32 v140, v19
	s_nop 0
	s_waitcnt lgkmcnt(1)
	v_mfma_f32_32x32x16_bf16 v[80:95], v[160:163], v[172:175], v[80:95]
	v_exp_f32_e32 v139, v20
	v_exp_f32_e32 v138, v21
	v_exp_f32_e32 v137, v22
	v_exp_f32_e32 v136, v23
	s_nop 0
	v_mfma_f32_32x32x16_bf16 v[96:111], v[148:151], v[168:171], v[96:111]
	v_exp_f32_e32 v123, v24
	v_exp_f32_e32 v122, v25
	v_exp_f32_e32 v121, v26
	v_exp_f32_e32 v120, v27
	s_nop 0
	s_waitcnt lgkmcnt(0)
	v_mfma_f32_32x32x16_bf16 v[80:95], v[164:167], v[168:171], v[80:95]
	v_exp_f32_e32 v127, v28
	v_exp_f32_e32 v126, v29
	v_exp_f32_e32 v125, v30
	v_exp_f32_e32 v124, v31
	s_nop 0
	s_waitcnt vmcnt(2)
	ds_write_b128 v208, v[68:71] offset:27648
	ds_write_b128 v208, v[64:67] offset:55296
	s_cbranch_scc1 .LBB0_681
	v_mad_i64_i32 v[16:17], s[26:27], v74, s55, 0
	s_add_u32 s26, s4, s19
	v_and_b32_e32 v18, 7, v76
	s_addc_u32 s27, s5, s18
	v_lshlrev_b32_e32 v200, 4, v18
	v_lshl_add_u64 v[202:203], s[26:27], 0, v[16:17]
	v_mov_b64_e32 v[30:31], v[14:15]
	v_mov_b64_e32 v[46:47], v[14:15]
	v_mov_b32_e32 v201, v0
	v_lshl_add_u64 v[204:205], s[26:27], 0, v[72:73]
	s_mov_b32 s27, 1
	v_mov_b32_e32 v64, 0
	s_mov_b32 s13, 12
	v_mov_b64_e32 v[28:29], v[12:13]
	v_mov_b64_e32 v[26:27], v[10:11]
	v_mov_b64_e32 v[24:25], v[8:9]
	v_mov_b64_e32 v[22:23], v[6:7]
	v_mov_b64_e32 v[20:21], v[4:5]
	v_mov_b64_e32 v[18:19], v[2:3]
	v_mov_b64_e32 v[16:17], v[0:1]
	v_mov_b64_e32 v[44:45], v[12:13]
	v_mov_b64_e32 v[42:43], v[10:11]
	v_mov_b64_e32 v[40:41], v[8:9]
	v_mov_b64_e32 v[38:39], v[6:7]
	v_mov_b64_e32 v[36:37], v[4:5]
	v_mov_b64_e32 v[34:35], v[2:3]
	v_mov_b64_e32 v[32:33], v[0:1]
	s_branch .LBB0_661
.Lle_a2_cont:
	s_mov_b32 s13, s28

.LBB0_663:
	s_add_i32 s28, s27, 1
	s_cmp_lg_u32 s27, 4
	s_cselect_b32 s27, s28, 0
	s_waitcnt lgkmcnt(6)
	v_mfma_f32_32x32x16_bf16 v[96:111], v[240:243], v[180:183], v[48:63]
	v_exp_f32_e32 v116, v136
	v_exp_f32_e32 v117, v137
	v_exp_f32_e32 v118, v138
	v_exp_f32_e32 v119, v139
	s_waitcnt lgkmcnt(5)
	v_mfma_f32_32x32x16_bf16 v[80:95], v[244:247], v[180:183], v[48:63]
	v_exp_f32_e32 v112, v140
	v_exp_f32_e32 v113, v141
	v_exp_f32_e32 v114, v142
	v_exp_f32_e32 v115, v143
	v_mfma_f32_32x32x16_bf16 v[96:111], v[164:167], v[176:179], v[96:111]
	v_exp_f32_e32 v187, v144
	v_exp_f32_e32 v186, v145
	v_exp_f32_e32 v185, v146
	v_exp_f32_e32 v184, v147
	s_waitcnt lgkmcnt(4)
	v_mfma_f32_32x32x16_bf16 v[80:95], v[160:163], v[176:179], v[80:95]
	v_exp_f32_e32 v147, v148
	v_exp_f32_e32 v146, v149
	v_exp_f32_e32 v145, v150
	v_exp_f32_e32 v144, v151
	s_waitcnt lgkmcnt(3)
	v_mfma_f32_32x32x16_bf16 v[96:111], v[74:77], v[172:175], v[96:111]
	v_exp_f32_e32 v143, v120
	v_exp_f32_e32 v142, v121
	v_exp_f32_e32 v141, v122
	v_exp_f32_e32 v140, v123
	s_waitcnt lgkmcnt(1)
	v_mfma_f32_32x32x16_bf16 v[80:95], v[70:73], v[172:175], v[80:95]
	v_exp_f32_e32 v139, v124
	v_exp_f32_e32 v138, v125
	v_exp_f32_e32 v137, v126
	v_exp_f32_e32 v136, v127
	v_mfma_f32_32x32x16_bf16 v[96:111], v[66:69], v[168:171], v[96:111]
	v_exp_f32_e32 v123, v128
	v_exp_f32_e32 v122, v129
	v_exp_f32_e32 v121, v130
	v_exp_f32_e32 v120, v131
	s_waitcnt lgkmcnt(0)
	v_mfma_f32_32x32x16_bf16 v[80:95], v[10:13], v[168:171], v[80:95]
	v_exp_f32_e32 v127, v132
	v_exp_f32_e32 v126, v133
	v_exp_f32_e32 v125, v134
	v_exp_f32_e32 v124, v135
	s_cmp_gt_i32 s27, 2
	s_cselect_b32 s28, -3, 2
	s_add_i32 s28, s28, s27
	s_mulk_i32 s28, 0x2400
	v_add_u32_e32 v1, s28, v208
	s_add_i32 s28, s27, 1
	s_cmp_lg_u32 s27, 4
	s_cselect_b32 s27, s28, 0
	s_add_i32 s28, s13, 8
	s_add_i32 s13, s13, 4
	s_cmp_ge_u32 s13, s2
	s_waitcnt vmcnt(3)
	ds_write_b128 v208, v[6:9] offset:27648
	s_waitcnt vmcnt(2)
	ds_write_b128 v1, v[2:5] offset:36864
	s_cbranch_scc0 .Lle_a2_cont
	s_branch .LBB0_682
